# non-temporal (nt) hint on the write-once epilogue stores of the two largest GEMM phases (gemm_a Z, ffn1 G), on top of v57
# speedup vs baseline: 1.0024x; 1.0024x over previous
; #define PG8_LDA(dst, b, h) do { _Pragma("unroll") for (int m = 0; m < 4; ++m) _Pragma("unroll") for (int k = 0; k < 2; ++k) dst[m][k] = *(const LAS bf16x8*)(lds + PG8_SA(b, h) + aoff + m * 2048 + k * 1024); } while (0)
; #define PG8_LDB(dst, b, h) do { _Pragma("unroll") for (int n = 0; n < 2; ++n) _Pragma("unroll") for (int k = 0; k < 2; ++k) dst[n][k] = *(const LAS bf16x8*)(lds + PG8_SB(b, h) + boff + n * 2048 + k * 1024); } while (0)
; #define PG8_MMA(ai, bj, At, Bt_) do { __builtin_amdgcn_s_setprio(1); _Pragma("unroll") for (int m = 0; m < 4; ++m) _Pragma("unroll") for (int n = 0; n < 2; ++n) _Pragma("unroll") for (int k = 0; k < 2; ++k) \
;     acc[ai][bj][m][n] = __builtin_amdgcn_mfma_f32_16x16x32_bf16(Bt_[n][k], At[m][k], acc[ai][bj][m][n], 0, 0, 0); __builtin_amdgcn_s_setprio(0); } while (0)
; #define PG8_WAIT_V(n) asm volatile("s_waitcnt vmcnt(" #n ")" ::: "memory")
; #define PG8_WAIT_L(n) asm volatile("s_waitcnt lgkmcnt(" #n ")" ::: "memory")
; #define PG8_BAR __builtin_amdgcn_s_barrier()
; #define PG8_SCHED __builtin_amdgcn_sched_barrier(0)
; #define PG8_STA(bufoff, gbase, ld2) PG8_STAGE3(bufoff, gbase, ld2, R0, R1)
; #define PG8_STB(bufoff, gbase, ld2) PG8_STAGE3(bufoff, gbase, ld2, Rb0, Rb1)
; #define PG8_LDA(dst, b, h) do { _Pragma("unroll") for (int m = 0; m < 4; ++m) _Pragma("unroll") for (int k = 0; k < 2; ++k) dst[m][k] = *(const LAS bf16x8*)(lds + PG8_SA(b, h) + aoff + m * 2048 + k * 1024); } while (0)
; #define PG8_LDB(dst, b, h) do { _Pragma("unroll") for (int n = 0; n < 2; ++n) _Pragma("unroll") for (int k = 0; k < 2; ++k) dst[n][k] = *(const LAS bf16x8*)(lds + PG8_SB(b, h) + boff + n * 2048 + k * 1024); } while (0)
; #define PG8_WAIT_V(n) asm volatile("s_waitcnt vmcnt(" #n ")" ::: "memory")
; template <class Sched, class Epi>
; DI void gemm_stream(char* smem, const Sched& S_, const Epi& E) {
;     ...
;       PG8_LDB(B0, 0, 0); PG8_SCHED; PG8_LDA(At, 0, 0); PG8_STA(PG8_SA(1, 1), a1 + hA, la2);
;       PG8_WAIT_L(8); PG8_BAR; PG8_WAIT_L(0); PG8_MMA(0, 0, At, B0); PG8_BAR; PG8_SCHED;
;       PG8_LDB(B1, 0, 1); PG8_STB(PG8_SB(0, 0), b2, xb2);
;       PG8_BAR; PG8_WAIT_L(0); PG8_MMA(0, 1, At, B1); PG8_BAR;
;       PG8_LDA(At, 0, 1); PG8_STA(PG8_SA(0, 0), a2, xa2);
;       PG8_BAR; PG8_WAIT_L(0); PG8_MMA(1, 0, At, B0); PG8_BAR; PG8_SCHED;
;       PG8_STB(PG8_SB(0, 1), b2 + xhB, xb2);
;       PG8_WAIT_V(6); PG8_BAR; PG8_MMA(1, 1, At, B1); PG8_BAR;
.LBB0_466:
	s_add_u32 s46, s44, 0xfffc0080
	s_addc_u32 s47, s45, -1
	s_add_i32 s52, 0, 0x10000
	v_add_u32_e32 v138, s52, v141
	ds_read_b128 v[144:147], v138
	ds_read_b128 v[148:151], v138 offset:1024
	ds_read_b128 v[152:155], v138 offset:2048
	ds_read_b128 v[156:159], v138 offset:3072
	s_cmp_eq_u32 s49, 12
	s_cselect_b32 s51, s37, s47
	s_cselect_b32 s50, s36, s46
	s_cselect_b32 s47, s41, s27
	s_cselect_b32 s46, s40, s1
	v_lshl_add_u64 v[138:139], s[44:45], 0, v[134:135]
	s_add_i32 m0, s5, 0xc000
	ds_read_b128 v[160:163], v143
	ds_read_b128 v[164:167], v143 offset:1024
	ds_read_b128 v[168:171], v143 offset:2048
	ds_read_b128 v[172:175], v143 offset:3072
	ds_read_b128 v[176:179], v143 offset:4096
	ds_read_b128 v[180:183], v143 offset:5120
	ds_read_b128 v[184:187], v143 offset:6144
	ds_read_b128 v[188:191], v143 offset:7168
	global_load_lds_dwordx4 v[138:139], off
	v_lshl_add_u64 v[138:139], s[44:45], 0, v[136:137]
	s_add_i32 m0, s5, 0xe000
	s_nop 0
	global_load_lds_dwordx4 v[138:139], off
	s_waitcnt lgkmcnt(8)
	s_barrier
	s_waitcnt lgkmcnt(0)
	s_setprio 1
	s_waitcnt lgkmcnt(0)
	v_mfma_f32_16x16x32_bf16 v[124:127], v[144:147], v[160:163], v[124:127]
	v_mfma_f32_16x16x32_bf16 v[120:123], v[152:155], v[160:163], v[120:123]
	v_mfma_f32_16x16x32_bf16 v[116:119], v[144:147], v[168:171], v[116:119]
	v_mfma_f32_16x16x32_bf16 v[112:115], v[152:155], v[168:171], v[112:115]
	v_mfma_f32_16x16x32_bf16 v[108:111], v[144:147], v[176:179], v[108:111]
	v_mfma_f32_16x16x32_bf16 v[100:103], v[152:155], v[176:179], v[100:103]
	v_mfma_f32_16x16x32_bf16 v[92:95], v[144:147], v[184:187], v[92:95]
	v_mfma_f32_16x16x32_bf16 v[84:87], v[152:155], v[184:187], v[84:87]
	v_mfma_f32_16x16x32_bf16 v[124:127], v[148:151], v[164:167], v[124:127]
	v_mfma_f32_16x16x32_bf16 v[120:123], v[156:159], v[164:167], v[120:123]
	v_mfma_f32_16x16x32_bf16 v[116:119], v[148:151], v[172:175], v[116:119]
	v_mfma_f32_16x16x32_bf16 v[112:115], v[156:159], v[172:175], v[112:115]
	v_mfma_f32_16x16x32_bf16 v[108:111], v[148:151], v[180:183], v[108:111]
	v_mfma_f32_16x16x32_bf16 v[100:103], v[156:159], v[180:183], v[100:103]
	v_mfma_f32_16x16x32_bf16 v[92:95], v[148:151], v[188:191], v[92:95]
	v_mfma_f32_16x16x32_bf16 v[84:87], v[156:159], v[188:191], v[84:87]
	s_setprio 0
	s_barrier
	s_add_i32 s56, 0, 0x14000
	v_add_u32_e32 v138, s56, v141
	s_add_i32 s52, s52, s4
	ds_read_b128 v[210:213], v138
	ds_read_b128 v[214:217], v138 offset:1024
	ds_read_b128 v[234:237], v138 offset:2048
	ds_read_b128 v[238:241], v138 offset:3072
	v_lshl_add_u64 v[138:139], s[46:47], 0, v[220:221]
	s_mov_b32 m0, s52
	v_lshl_add_u64 v[218:219], s[46:47], 0, v[128:129]
	global_load_lds_dwordx4 v[138:139], off
	s_add_i32 m0, s52, 0x2000
	s_nop 0
	global_load_lds_dwordx4 v[218:219], off
	s_barrier
	s_waitcnt lgkmcnt(0)
	s_setprio 1
	s_waitcnt lgkmcnt(0)
	v_mfma_f32_16x16x32_bf16 v[104:107], v[210:213], v[160:163], v[104:107]
	v_mfma_f32_16x16x32_bf16 v[96:99], v[234:237], v[160:163], v[96:99]
	v_mfma_f32_16x16x32_bf16 v[88:91], v[210:213], v[168:171], v[88:91]
	v_mfma_f32_16x16x32_bf16 v[80:83], v[234:237], v[168:171], v[80:83]
	v_mfma_f32_16x16x32_bf16 v[76:79], v[210:213], v[176:179], v[76:79]
	v_mfma_f32_16x16x32_bf16 v[72:75], v[234:237], v[176:179], v[72:75]
	v_mfma_f32_16x16x32_bf16 v[68:71], v[210:213], v[184:187], v[68:71]
	v_mfma_f32_16x16x32_bf16 v[64:67], v[234:237], v[184:187], v[64:67]
	v_mfma_f32_16x16x32_bf16 v[104:107], v[214:217], v[164:167], v[104:107]
	v_mfma_f32_16x16x32_bf16 v[96:99], v[238:241], v[164:167], v[96:99]
	v_mfma_f32_16x16x32_bf16 v[88:91], v[214:217], v[172:175], v[88:91]
	v_mfma_f32_16x16x32_bf16 v[80:83], v[238:241], v[172:175], v[80:83]
	v_mfma_f32_16x16x32_bf16 v[76:79], v[214:217], v[180:183], v[76:79]
	v_mfma_f32_16x16x32_bf16 v[72:75], v[238:241], v[180:183], v[72:75]
	v_mfma_f32_16x16x32_bf16 v[68:71], v[214:217], v[188:191], v[68:71]
	v_mfma_f32_16x16x32_bf16 v[64:67], v[238:241], v[188:191], v[64:67]
	s_setprio 0
	s_mov_b32 m0, s5
	v_lshl_add_u64 v[242:243], s[50:51], 0, v[130:131]
	s_barrier
	ds_read_b128 v[160:163], v143 offset:16384
	ds_read_b128 v[164:167], v143 offset:17408
	ds_read_b128 v[168:171], v143 offset:18432
	ds_read_b128 v[172:175], v143 offset:19456
	ds_read_b128 v[176:179], v143 offset:20480
	ds_read_b128 v[180:183], v143 offset:21504
	ds_read_b128 v[184:187], v143 offset:22528
	ds_read_b128 v[188:191], v143 offset:23552
	global_load_lds_dwordx4 v[242:243], off
	v_lshl_add_u64 v[244:245], s[50:51], 0, v[132:133]
	s_mov_b32 m0, s9
	s_nop 0
	global_load_lds_dwordx4 v[244:245], off
	s_barrier
	s_waitcnt lgkmcnt(0)
	s_setprio 1
	s_waitcnt lgkmcnt(0)
	v_mfma_f32_16x16x32_bf16 v[60:63], v[144:147], v[160:163], v[60:63]
	v_mfma_f32_16x16x32_bf16 v[56:59], v[152:155], v[160:163], v[56:59]
	v_mfma_f32_16x16x32_bf16 v[52:55], v[144:147], v[168:171], v[52:55]
	v_mfma_f32_16x16x32_bf16 v[48:51], v[152:155], v[168:171], v[48:51]
	v_mfma_f32_16x16x32_bf16 v[44:47], v[144:147], v[176:179], v[44:47]
	v_mfma_f32_16x16x32_bf16 v[36:39], v[152:155], v[176:179], v[36:39]
	v_mfma_f32_16x16x32_bf16 v[28:31], v[144:147], v[184:187], v[28:31]
	v_mfma_f32_16x16x32_bf16 v[20:23], v[152:155], v[184:187], v[20:23]
	v_mfma_f32_16x16x32_bf16 v[60:63], v[148:151], v[164:167], v[60:63]
	v_mfma_f32_16x16x32_bf16 v[56:59], v[156:159], v[164:167], v[56:59]
	v_mfma_f32_16x16x32_bf16 v[52:55], v[148:151], v[172:175], v[52:55]
	v_mfma_f32_16x16x32_bf16 v[48:51], v[156:159], v[172:175], v[48:51]
	v_mfma_f32_16x16x32_bf16 v[44:47], v[148:151], v[180:183], v[44:47]
	v_mfma_f32_16x16x32_bf16 v[36:39], v[156:159], v[180:183], v[36:39]
	v_mfma_f32_16x16x32_bf16 v[28:31], v[148:151], v[188:191], v[28:31]
	v_mfma_f32_16x16x32_bf16 v[20:23], v[156:159], v[188:191], v[20:23]
	s_setprio 0
	s_barrier
; #define PG8_LDA(dst, b, h) do { _Pragma("unroll") for (int m = 0; m < 4; ++m) _Pragma("unroll") for (int k = 0; k < 2; ++k) dst[m][k] = *(const LAS bf16x8*)(lds + PG8_SA(b, h) + aoff + m * 2048 + k * 1024); } while (0)
; #define PG8_LDB(dst, b, h) do { _Pragma("unroll") for (int n = 0; n < 2; ++n) _Pragma("unroll") for (int k = 0; k < 2; ++k) dst[n][k] = *(const LAS bf16x8*)(lds + PG8_SB(b, h) + boff + n * 2048 + k * 1024); } while (0)
; #define PG8_MMA(ai, bj, At, Bt_) do { __builtin_amdgcn_s_setprio(1); _Pragma("unroll") for (int m = 0; m < 4; ++m) _Pragma("unroll") for (int n = 0; n < 2; ++n) _Pragma("unroll") for (int k = 0; k < 2; ++k) \
;     acc[ai][bj][m][n] = __builtin_amdgcn_mfma_f32_16x16x32_bf16(Bt_[n][k], At[m][k], acc[ai][bj][m][n], 0, 0, 0); __builtin_amdgcn_s_setprio(0); } while (0)
; #define PG8_WAIT_V(n) asm volatile("s_waitcnt vmcnt(" #n ")" ::: "memory")
; #define PG8_WAIT_L(n) asm volatile("s_waitcnt lgkmcnt(" #n ")" ::: "memory")
; #define PG8_BAR __builtin_amdgcn_s_barrier()
; #define PG8_SCHED __builtin_amdgcn_sched_barrier(0)
; #define PG8_STA(bufoff, gbase, ld2) PG8_STAGE3(bufoff, gbase, ld2, R0, R1)
; #define PG8_STB(bufoff, gbase, ld2) PG8_STAGE3(bufoff, gbase, ld2, Rb0, Rb1)
; #define PG8_LDA(dst, b, h) do { _Pragma("unroll") for (int m = 0; m < 4; ++m) _Pragma("unroll") for (int k = 0; k < 2; ++k) dst[m][k] = *(const LAS bf16x8*)(lds + PG8_SA(b, h) + aoff + m * 2048 + k * 1024); } while (0)
; #define PG8_WAIT_V(n) asm volatile("s_waitcnt vmcnt(" #n ")" ::: "memory")
; #define PG8_WAIT_L(n) asm volatile("s_waitcnt lgkmcnt(" #n ")" ::: "memory")
; template <class Sched, class Epi>
; DI void gemm_stream(char* smem, const Sched& S_, const Epi& E) {
;     ...
;       PG8_LDA(At, 0, 1); PG8_STA(PG8_SA(0, 0), a2, xa2);
;       PG8_BAR; PG8_WAIT_L(0); PG8_MMA(1, 0, At, B0); PG8_BAR; PG8_SCHED;
;       PG8_STB(PG8_SB(0, 1), b2 + xhB, xb2);
;       PG8_WAIT_V(6); PG8_BAR; PG8_MMA(1, 1, At, B1); PG8_BAR;
;       PG8_LDB(B0, 1, 0); PG8_SCHED; PG8_LDA(At, 1, 0); PG8_STA(PG8_SA(0, 1), a2 + xhA, xa2);
;       PG8_WAIT_L(8); PG8_BAR; PG8_WAIT_L(0); PG8_MMA(0, 0, At, B0); PG8_BAR; PG8_SCHED;
;       PG8_LDB(B1, 1, 1); PG8_STB(PG8_SB(1, 0), b3, xb2);
;       PG8_BAR; PG8_WAIT_L(0); PG8_MMA(0, 1, At, B1); PG8_BAR;
;       PG8_LDA(At, 1, 1); PG8_STA(PG8_SA(1, 0), a3, xa2);
;       PG8_BAR; PG8_WAIT_L(0); PG8_MMA(1, 0, At, B0); PG8_BAR; PG8_SCHED;
	s_add_u32 s52, s46, 0x40000
	s_addc_u32 s53, s47, 0
	s_add_i32 s56, s56, s4
	v_lshl_add_u64 v[144:145], s[52:53], 0, v[220:221]
	s_mov_b32 m0, s56
	s_nop 0
	global_load_lds_dwordx4 v[144:145], off
	v_lshl_add_u64 v[144:145], s[52:53], 0, v[128:129]
	s_add_i32 m0, s56, 0x2000
	s_nop 0
	global_load_lds_dwordx4 v[144:145], off
	s_waitcnt vmcnt(6)
	s_barrier
	s_setprio 1
	v_mfma_f32_16x16x32_bf16 v[40:43], v[210:213], v[160:163], v[40:43]
	v_mfma_f32_16x16x32_bf16 v[32:35], v[234:237], v[160:163], v[32:35]
	v_mfma_f32_16x16x32_bf16 v[24:27], v[210:213], v[168:171], v[24:27]
	v_mfma_f32_16x16x32_bf16 v[16:19], v[234:237], v[168:171], v[16:19]
	v_mfma_f32_16x16x32_bf16 v[12:15], v[210:213], v[176:179], v[12:15]
	v_mfma_f32_16x16x32_bf16 v[8:11], v[234:237], v[176:179], v[8:11]
	v_mfma_f32_16x16x32_bf16 v[4:7], v[210:213], v[184:187], v[4:7]
	v_mfma_f32_16x16x32_bf16 v[0:3], v[234:237], v[184:187], v[0:3]
	v_mfma_f32_16x16x32_bf16 v[40:43], v[214:217], v[164:167], v[40:43]
	v_mfma_f32_16x16x32_bf16 v[32:35], v[238:241], v[164:167], v[32:35]
	v_mfma_f32_16x16x32_bf16 v[24:27], v[214:217], v[172:175], v[24:27]
	v_mfma_f32_16x16x32_bf16 v[16:19], v[238:241], v[172:175], v[16:19]
	v_mfma_f32_16x16x32_bf16 v[12:15], v[214:217], v[180:183], v[12:15]
	v_mfma_f32_16x16x32_bf16 v[8:11], v[238:241], v[180:183], v[8:11]
	v_mfma_f32_16x16x32_bf16 v[4:7], v[214:217], v[188:191], v[4:7]
	v_mfma_f32_16x16x32_bf16 v[0:3], v[238:241], v[188:191], v[0:3]
	s_setprio 0
	s_add_i32 s52, 0, 0x18000
	v_add_u32_e32 v156, s52, v141
	s_barrier
	ds_read_b128 v[144:147], v156
	ds_read_b128 v[148:151], v156 offset:1024
	ds_read_b128 v[152:155], v156 offset:2048
	ds_read_b128 v[156:159], v156 offset:3072
	s_add_u32 s50, s50, 0x40000
	s_addc_u32 s51, s51, 0
	s_mov_b32 m0, s13
	v_lshl_add_u64 v[210:211], s[50:51], 0, v[130:131]
	ds_read_b128 v[160:163], v143 offset:32768
	ds_read_b128 v[164:167], v143 offset:33792
	ds_read_b128 v[168:171], v143 offset:34816
	ds_read_b128 v[172:175], v143 offset:35840
	ds_read_b128 v[176:179], v143 offset:36864
	ds_read_b128 v[180:183], v143 offset:37888
	ds_read_b128 v[184:187], v143 offset:38912
	ds_read_b128 v[188:191], v143 offset:39936
	global_load_lds_dwordx4 v[210:211], off
	v_lshl_add_u64 v[210:211], s[50:51], 0, v[132:133]
	s_mov_b32 m0, s15
	s_nop 0
	global_load_lds_dwordx4 v[210:211], off
	s_waitcnt lgkmcnt(8)
	s_barrier
	s_waitcnt lgkmcnt(0)
	s_setprio 1
	s_waitcnt lgkmcnt(0)
	v_mfma_f32_16x16x32_bf16 v[124:127], v[144:147], v[160:163], v[124:127]
	v_mfma_f32_16x16x32_bf16 v[120:123], v[152:155], v[160:163], v[120:123]
	v_mfma_f32_16x16x32_bf16 v[116:119], v[144:147], v[168:171], v[116:119]
	v_mfma_f32_16x16x32_bf16 v[112:115], v[152:155], v[168:171], v[112:115]
	v_mfma_f32_16x16x32_bf16 v[108:111], v[144:147], v[176:179], v[108:111]
	v_mfma_f32_16x16x32_bf16 v[100:103], v[152:155], v[176:179], v[100:103]
	v_mfma_f32_16x16x32_bf16 v[92:95], v[144:147], v[184:187], v[92:95]
	v_mfma_f32_16x16x32_bf16 v[84:87], v[152:155], v[184:187], v[84:87]
	v_mfma_f32_16x16x32_bf16 v[124:127], v[148:151], v[164:167], v[124:127]
	v_mfma_f32_16x16x32_bf16 v[120:123], v[156:159], v[164:167], v[120:123]
	v_mfma_f32_16x16x32_bf16 v[116:119], v[148:151], v[172:175], v[116:119]
	v_mfma_f32_16x16x32_bf16 v[112:115], v[156:159], v[172:175], v[112:115]
	v_mfma_f32_16x16x32_bf16 v[108:111], v[148:151], v[180:183], v[108:111]
	v_mfma_f32_16x16x32_bf16 v[100:103], v[156:159], v[180:183], v[100:103]
	v_mfma_f32_16x16x32_bf16 v[92:95], v[148:151], v[188:191], v[92:95]
	v_mfma_f32_16x16x32_bf16 v[84:87], v[156:159], v[188:191], v[84:87]
	s_setprio 0
	s_barrier
	s_add_i32 s50, 0, 0x1c000
	s_add_i32 s51, s52, s4
	v_add_u32_e32 v194, s50, v141
	v_lshl_add_u64 v[138:139], v[138:139], 0, s[58:59]
	s_mov_b32 m0, s51
	ds_read_b128 v[210:213], v194
	ds_read_b128 v[214:217], v194 offset:1024
	ds_read_b128 v[234:237], v194 offset:2048
	ds_read_b128 v[238:241], v194 offset:3072
	global_load_lds_dwordx4 v[138:139], off
	v_lshl_add_u64 v[138:139], v[218:219], 0, s[58:59]
	s_add_i32 m0, s51, 0x2000
	s_nop 0
	global_load_lds_dwordx4 v[138:139], off
	s_barrier
	s_waitcnt lgkmcnt(0)
	s_setprio 1
	s_waitcnt lgkmcnt(0)
	v_mfma_f32_16x16x32_bf16 v[104:107], v[210:213], v[160:163], v[104:107]
	v_mfma_f32_16x16x32_bf16 v[96:99], v[234:237], v[160:163], v[96:99]
	v_mfma_f32_16x16x32_bf16 v[88:91], v[210:213], v[168:171], v[88:91]
	v_mfma_f32_16x16x32_bf16 v[80:83], v[234:237], v[168:171], v[80:83]
	v_mfma_f32_16x16x32_bf16 v[76:79], v[210:213], v[176:179], v[76:79]
	v_mfma_f32_16x16x32_bf16 v[72:75], v[234:237], v[176:179], v[72:75]
	v_mfma_f32_16x16x32_bf16 v[68:71], v[210:213], v[184:187], v[68:71]
	v_mfma_f32_16x16x32_bf16 v[64:67], v[234:237], v[184:187], v[64:67]
	v_mfma_f32_16x16x32_bf16 v[104:107], v[214:217], v[164:167], v[104:107]
	v_mfma_f32_16x16x32_bf16 v[96:99], v[238:241], v[164:167], v[96:99]
	v_mfma_f32_16x16x32_bf16 v[88:91], v[214:217], v[172:175], v[88:91]
	v_mfma_f32_16x16x32_bf16 v[80:83], v[238:241], v[172:175], v[80:83]
	v_mfma_f32_16x16x32_bf16 v[76:79], v[214:217], v[180:183], v[76:79]
	v_mfma_f32_16x16x32_bf16 v[72:75], v[238:241], v[180:183], v[72:75]
	v_mfma_f32_16x16x32_bf16 v[68:71], v[214:217], v[188:191], v[68:71]
	v_mfma_f32_16x16x32_bf16 v[64:67], v[238:241], v[188:191], v[64:67]
	s_setprio 0
	s_mov_b32 m0, s16
	v_lshl_add_u64 v[138:139], v[242:243], 0, s[58:59]
	s_barrier
	ds_read_b128 v[160:163], v143 offset:49152
	ds_read_b128 v[164:167], v143 offset:50176
	ds_read_b128 v[168:171], v143 offset:51200
	ds_read_b128 v[172:175], v143 offset:52224
	ds_read_b128 v[176:179], v143 offset:53248
	ds_read_b128 v[180:183], v143 offset:54272
	ds_read_b128 v[184:187], v143 offset:55296
	ds_read_b128 v[188:191], v143 offset:56320
	global_load_lds_dwordx4 v[138:139], off
	v_lshl_add_u64 v[138:139], v[244:245], 0, s[58:59]
	s_mov_b32 m0, s20
	s_nop 0
	global_load_lds_dwordx4 v[138:139], off
	s_barrier
; DI unsigned pk2(float a, float b) { f2_t v = {a, b}; bf2_t r = __builtin_convertvector(v, bf2_t); return __builtin_bit_cast(unsigned, r); }
; #define PG8_LDA(dst, b, h) do { _Pragma("unroll") for (int m = 0; m < 4; ++m) _Pragma("unroll") for (int k = 0; k < 2; ++k) dst[m][k] = *(const LAS bf16x8*)(lds + PG8_SA(b, h) + aoff + m * 2048 + k * 1024); } while (0)
; #define PG8_MMA(ai, bj, At, Bt_) do { __builtin_amdgcn_s_setprio(1); _Pragma("unroll") for (int m = 0; m < 4; ++m) _Pragma("unroll") for (int n = 0; n < 2; ++n) _Pragma("unroll") for (int k = 0; k < 2; ++k) \
;     acc[ai][bj][m][n] = __builtin_amdgcn_mfma_f32_16x16x32_bf16(Bt_[n][k], At[m][k], acc[ai][bj][m][n], 0, 0, 0); __builtin_amdgcn_s_setprio(0); } while (0)
; #define PG8_WAIT_V(n) asm volatile("s_waitcnt vmcnt(" #n ")" ::: "memory")
; #define PG8_WAIT_L(n) asm volatile("s_waitcnt lgkmcnt(" #n ")" ::: "memory")
; #define PG8_BAR __builtin_amdgcn_s_barrier()
; #define PG8_SCHED __builtin_amdgcn_sched_barrier(0)
; #define PG8_STA(bufoff, gbase, ld2) PG8_STAGE3(bufoff, gbase, ld2, R0, R1)
; #define PG8_STB(bufoff, gbase, ld2) PG8_STAGE3(bufoff, gbase, ld2, Rb0, Rb1)
; #define PG8_LDA(dst, b, h) do { _Pragma("unroll") for (int m = 0; m < 4; ++m) _Pragma("unroll") for (int k = 0; k < 2; ++k) dst[m][k] = *(const LAS bf16x8*)(lds + PG8_SA(b, h) + aoff + m * 2048 + k * 1024); } while (0)
; #define PG8_MMA(ai, bj, At, Bt_) do { __builtin_amdgcn_s_setprio(1); _Pragma("unroll") for (int m = 0; m < 4; ++m) _Pragma("unroll") for (int n = 0; n < 2; ++n) _Pragma("unroll") for (int k = 0; k < 2; ++k) \
;     acc[ai][bj][m][n] = __builtin_amdgcn_mfma_f32_16x16x32_bf16(Bt_[n][k], At[m][k], acc[ai][bj][m][n], 0, 0, 0); __builtin_amdgcn_s_setprio(0); } while (0)
; #define PG8_WAIT_V(n) asm volatile("s_waitcnt vmcnt(" #n ")" ::: "memory")
; DI u32x4 pack8v(const f32x4& a, const f32x4& b) { u32x4 w; w.x = pk2(a[0], a[1]); w.y = pk2(a[2], a[3]); w.z = pk2(b[0], b[1]); w.w = pk2(b[2], b[3]); return w; }
; template <class Sched, class Epi>
; DI void gemm_stream(char* smem, const Sched& S_, const Epi& E) {
;     ...
;       PG8_LDA(At, 1, 1); PG8_STA(PG8_SA(1, 0), a3, xa2);
;       PG8_BAR; PG8_WAIT_L(0); PG8_MMA(1, 0, At, B0); PG8_BAR; PG8_SCHED;
;       PG8_STB(PG8_SB(1, 1), b3 + xhB, xb2);
;       PG8_WAIT_V(6); PG8_BAR; PG8_MMA(1, 1, At, B1); PG8_BAR;
;     }
;     E(acc, cur, wr, wc, fr, fq);
	s_waitcnt lgkmcnt(0)
	s_setprio 1
	s_waitcnt lgkmcnt(0)
	v_mfma_f32_16x16x32_bf16 v[60:63], v[144:147], v[160:163], v[60:63]
	v_mfma_f32_16x16x32_bf16 v[56:59], v[152:155], v[160:163], v[56:59]
	v_mfma_f32_16x16x32_bf16 v[52:55], v[144:147], v[168:171], v[52:55]
	v_mfma_f32_16x16x32_bf16 v[48:51], v[152:155], v[168:171], v[48:51]
	v_mfma_f32_16x16x32_bf16 v[44:47], v[144:147], v[176:179], v[44:47]
	v_mfma_f32_16x16x32_bf16 v[36:39], v[152:155], v[176:179], v[36:39]
	v_mfma_f32_16x16x32_bf16 v[28:31], v[144:147], v[184:187], v[28:31]
	v_mfma_f32_16x16x32_bf16 v[20:23], v[152:155], v[184:187], v[20:23]
	v_mfma_f32_16x16x32_bf16 v[60:63], v[148:151], v[164:167], v[60:63]
	v_mfma_f32_16x16x32_bf16 v[56:59], v[156:159], v[164:167], v[56:59]
	v_mfma_f32_16x16x32_bf16 v[52:55], v[148:151], v[172:175], v[52:55]
	v_mfma_f32_16x16x32_bf16 v[48:51], v[156:159], v[172:175], v[48:51]
	v_mfma_f32_16x16x32_bf16 v[44:47], v[148:151], v[180:183], v[44:47]
	v_mfma_f32_16x16x32_bf16 v[36:39], v[156:159], v[180:183], v[36:39]
	v_mfma_f32_16x16x32_bf16 v[28:31], v[148:151], v[188:191], v[28:31]
	v_mfma_f32_16x16x32_bf16 v[20:23], v[156:159], v[188:191], v[20:23]
	s_setprio 0
	s_barrier
	s_add_u32 s46, s46, 0x40080
	s_addc_u32 s47, s47, 0
	s_add_i32 s50, s50, s4
	v_lshl_add_u64 v[138:139], s[46:47], 0, v[220:221]
	s_mov_b32 m0, s50
	s_nop 0
	global_load_lds_dwordx4 v[138:139], off
	v_lshl_add_u64 v[138:139], s[46:47], 0, v[128:129]
	s_add_i32 m0, s50, 0x2000
	s_nop 0
	global_load_lds_dwordx4 v[138:139], off
	s_waitcnt vmcnt(6)
	s_barrier
	s_setprio 1
	v_mfma_f32_16x16x32_bf16 v[40:43], v[210:213], v[160:163], v[40:43]
	v_mfma_f32_16x16x32_bf16 v[32:35], v[234:237], v[160:163], v[32:35]
	v_mfma_f32_16x16x32_bf16 v[24:27], v[210:213], v[168:171], v[24:27]
	v_mfma_f32_16x16x32_bf16 v[16:19], v[234:237], v[168:171], v[16:19]
	v_mfma_f32_16x16x32_bf16 v[12:15], v[210:213], v[176:179], v[12:15]
	v_mfma_f32_16x16x32_bf16 v[8:11], v[234:237], v[176:179], v[8:11]
	v_mfma_f32_16x16x32_bf16 v[4:7], v[210:213], v[184:187], v[4:7]
	v_mfma_f32_16x16x32_bf16 v[0:3], v[234:237], v[184:187], v[0:3]
	v_mfma_f32_16x16x32_bf16 v[40:43], v[214:217], v[164:167], v[40:43]
	v_mfma_f32_16x16x32_bf16 v[32:35], v[238:241], v[164:167], v[32:35]
	v_mfma_f32_16x16x32_bf16 v[24:27], v[214:217], v[172:175], v[24:27]
	v_mfma_f32_16x16x32_bf16 v[16:19], v[238:241], v[172:175], v[16:19]
	v_mfma_f32_16x16x32_bf16 v[12:15], v[214:217], v[180:183], v[12:15]
	v_mfma_f32_16x16x32_bf16 v[8:11], v[238:241], v[180:183], v[8:11]
	v_mfma_f32_16x16x32_bf16 v[4:7], v[214:217], v[188:191], v[4:7]
	v_mfma_f32_16x16x32_bf16 v[0:3], v[238:241], v[188:191], v[0:3]
	s_setprio 0
	s_add_i32 s49, s49, 2
	s_add_u32 s44, s44, 0x100
	s_addc_u32 s45, s45, 0
	s_add_u32 s1, s1, 0x100
	s_addc_u32 s27, s27, 0
	s_cmp_gt_u32 s49, 13
	s_barrier
	s_cbranch_scc0 .LBB0_466
	s_lshl_b32 s1, s33, 8
	v_lshl_add_u32 v138, s43, 8, v140
	s_cmp_lg_u32 s42, 0
	v_cvt_pk_bf16_f32 v124, v124, v125
	v_cvt_pk_bf16_f32 v125, v126, v127
	v_cvt_pk_bf16_f32 v126, v120, v121
	v_cvt_pk_bf16_f32 v127, v122, v123
	v_cvt_pk_bf16_f32 v104, v104, v105
	v_cvt_pk_bf16_f32 v105, v106, v107
	v_cvt_pk_bf16_f32 v106, v96, v97
	v_cvt_pk_bf16_f32 v107, v98, v99
	v_cvt_pk_bf16_f32 v96, v116, v117
	v_cvt_pk_bf16_f32 v97, v118, v119
	v_cvt_pk_bf16_f32 v98, v112, v113
	v_cvt_pk_bf16_f32 v99, v114, v115
	v_cvt_pk_bf16_f32 v88, v88, v89
	v_cvt_pk_bf16_f32 v89, v90, v91
	v_cvt_pk_bf16_f32 v90, v80, v81
	v_cvt_pk_bf16_f32 v91, v82, v83
	v_cvt_pk_bf16_f32 v80, v108, v109
	v_cvt_pk_bf16_f32 v81, v110, v111
	v_cvt_pk_bf16_f32 v82, v100, v101
	v_cvt_pk_bf16_f32 v83, v102, v103
	v_cvt_pk_bf16_f32 v76, v76, v77
	v_cvt_pk_bf16_f32 v77, v78, v79
	v_cvt_pk_bf16_f32 v78, v72, v73
	v_cvt_pk_bf16_f32 v79, v74, v75
	v_cvt_pk_bf16_f32 v72, v92, v93
	v_cvt_pk_bf16_f32 v73, v94, v95
	v_cvt_pk_bf16_f32 v74, v84, v85
	v_cvt_pk_bf16_f32 v75, v86, v87
	v_cvt_pk_bf16_f32 v68, v68, v69
	v_cvt_pk_bf16_f32 v69, v70, v71
	v_cvt_pk_bf16_f32 v70, v64, v65
	v_cvt_pk_bf16_f32 v71, v66, v67
	v_cvt_pk_bf16_f32 v60, v60, v61
	v_cvt_pk_bf16_f32 v61, v62, v63
	v_cvt_pk_bf16_f32 v62, v56, v57
	v_cvt_pk_bf16_f32 v63, v58, v59
	v_cvt_pk_bf16_f32 v40, v40, v41
	v_cvt_pk_bf16_f32 v41, v42, v43
	v_cvt_pk_bf16_f32 v42, v32, v33
	v_cvt_pk_bf16_f32 v43, v34, v35
	v_cvt_pk_bf16_f32 v32, v52, v53
	v_cvt_pk_bf16_f32 v33, v54, v55
	v_cvt_pk_bf16_f32 v34, v48, v49
	v_cvt_pk_bf16_f32 v35, v50, v51
	v_cvt_pk_bf16_f32 v24, v24, v25
	v_cvt_pk_bf16_f32 v25, v26, v27
	v_cvt_pk_bf16_f32 v26, v16, v17
	v_cvt_pk_bf16_f32 v27, v18, v19
	v_cvt_pk_bf16_f32 v16, v44, v45
	v_cvt_pk_bf16_f32 v17, v46, v47
	v_cvt_pk_bf16_f32 v18, v36, v37
	v_cvt_pk_bf16_f32 v19, v38, v39
	v_cvt_pk_bf16_f32 v12, v12, v13
	v_cvt_pk_bf16_f32 v13, v14, v15
	v_cvt_pk_bf16_f32 v14, v8, v9
	v_cvt_pk_bf16_f32 v15, v10, v11
	v_cvt_pk_bf16_f32 v8, v28, v29
	v_cvt_pk_bf16_f32 v9, v30, v31
	v_cvt_pk_bf16_f32 v10, v20, v21
	v_cvt_pk_bf16_f32 v11, v22, v23
	v_readlane_b32 s49, v254, 50
	s_cbranch_scc0 .LBB0_469
; DI u32x4 pack8v(const f32x4& a, const f32x4& b) { u32x4 w; w.x = pk2(a[0], a[1]); w.y = pk2(a[2], a[3]); w.z = pk2(b[0], b[1]); w.w = pk2(b[2], b[3]); return w; }
;   DI void operator()(const acc_t& acc, const Desc& u, int wr, int wc, int fr, int fq) const {
;     ...
;       const int t0 = u.pn * BM, b = t0 / S, s0 = t0 - b * S + wc * 32 + 8 * fq;
; #pragma unroll
;       for (int ai = 0; ai < 2; ++ai)
; #pragma unroll
;         for (int m = 0; m < 4; ++m) { bf16_t* rowp = RVT + ((size_t)b * 512 + row0 + ai * HALF + m * 16) * S + s0;
; #pragma unroll
;           for (int bj = 0; bj < 2; ++bj) *(u32x4*)(rowp + bj * HALF) = pack8v(acc[ai][bj][m][0], acc[ai][bj][m][1]); }
	s_mul_hi_i32 s27, s33, 0x78787879
	s_lshr_b32 s33, s27, 31
	s_ashr_i32 s27, s27, 3
	s_add_i32 s42, s27, s33
	s_ashr_i32 s43, s42, 31
	s_mul_i32 s27, s42, 0xffffef00
	s_lshl_b64 s[42:43], s[42:43], 9
	v_ashrrev_i32_e32 v139, 31, v138
	v_lshl_add_u64 v[22:23], s[42:43], 0, v[138:139]
	v_readlane_b32 s42, v251, 41
	s_add_i32 s27, s27, s1
	v_readlane_b32 s43, v251, 42
	v_or_b32_e32 v20, s27, v142
	s_movk_i32 s27, 0x2200
	v_mov_b64_e32 v[28:29], s[42:43]
	v_mad_u64_u32 v[28:29], s[42:43], v22, s27, v[28:29]
	v_ashrrev_i32_e32 v21, 31, v20
	v_mad_i32_i24 v29, v23, s27, v29
	v_lshl_add_u64 v[22:23], v[20:21], 1, v[28:29]
	s_mov_b32 s27, 0x22000
	v_add_co_u32_e32 v28, vcc, s27, v22
	s_mov_b64 s[42:43], 0x22000
	s_nop 0
	v_addc_co_u32_e32 v29, vcc, 0, v23, vcc
	s_mov_b32 s27, 0x44000
	global_store_dwordx4 v[22:23], v[124:127], off nt
	global_store_dwordx4 v[22:23], v[104:107], off offset:256 nt
	v_lshl_add_u64 v[20:21], v[22:23], 0, s[42:43]
	global_store_dwordx4 v[28:29], v[96:99], off nt
	global_store_dwordx4 v[20:21], v[88:91], off offset:256 nt
	v_add_co_u32_e32 v28, vcc, s27, v22
	s_mov_b64 s[42:43], 0x44000
	s_nop 0
	v_addc_co_u32_e32 v29, vcc, 0, v23, vcc
	s_mov_b32 s27, 0x66000
	v_lshl_add_u64 v[20:21], v[22:23], 0, s[42:43]
	global_store_dwordx4 v[28:29], v[80:83], off nt
	global_store_dwordx4 v[20:21], v[76:79], off offset:256 nt
	v_add_co_u32_e32 v28, vcc, s27, v22
	s_mov_b64 s[42:43], 0x66000
	s_nop 0
	v_addc_co_u32_e32 v29, vcc, 0, v23, vcc
	s_mov_b32 s27, 0x110000
	v_lshl_add_u64 v[20:21], v[22:23], 0, s[42:43]
	global_store_dwordx4 v[28:29], v[72:75], off nt
	global_store_dwordx4 v[20:21], v[68:71], off offset:256 nt
	v_add_co_u32_e32 v28, vcc, s27, v22
	s_mov_b64 s[42:43], 0x110000
	s_nop 0
	v_addc_co_u32_e32 v29, vcc, 0, v23, vcc
	s_mov_b32 s27, 0x132000
	v_lshl_add_u64 v[20:21], v[22:23], 0, s[42:43]
	global_store_dwordx4 v[28:29], v[60:63], off nt
	global_store_dwordx4 v[20:21], v[40:43], off offset:256 nt
	v_add_co_u32_e32 v28, vcc, s27, v22
	s_mov_b64 s[42:43], 0x132000
	s_nop 0
	v_addc_co_u32_e32 v29, vcc, 0, v23, vcc
	s_mov_b32 s27, 0x154000
	v_lshl_add_u64 v[20:21], v[22:23], 0, s[42:43]
	global_store_dwordx4 v[28:29], v[32:35], off nt
	global_store_dwordx4 v[20:21], v[24:27], off offset:256 nt
	s_mov_b64 s[42:43], 0x154000
	v_add_co_u32_e32 v28, vcc, s27, v22
	v_lshl_add_u64 v[20:21], v[22:23], 0, s[42:43]
	s_nop 0
	v_addc_co_u32_e32 v29, vcc, 0, v23, vcc
	s_mov_b64 s[42:43], 0x176000
	global_store_dwordx4 v[28:29], v[16:19], off nt
	global_store_dwordx4 v[20:21], v[12:15], off offset:256 nt
	v_lshl_add_u64 v[20:21], v[22:23], 0, s[42:43]
	v_add_co_u32_e32 v22, vcc, 0x176000, v22
	s_nop 1
	v_addc_co_u32_e32 v23, vcc, 0, v23, vcc
	global_store_dwordx4 v[22:23], v[8:11], off nt
	s_movk_i32 s50, 0x100
	s_mov_b32 s51, 0x78787879
	s_cbranch_execnz .LBB0_456
	s_branch .LBB0_470

; DI u32x4 pack8v(const f32x4& a, const f32x4& b) { u32x4 w; w.x = pk2(a[0], a[1]); w.y = pk2(a[2], a[3]); w.z = pk2(b[0], b[1]); w.w = pk2(b[2], b[3]); return w; }
;   DI void operator()(const acc_t& acc, const Desc& u, int wr, int wc, int fr, int fq) const {
;     ...
;       const int col0 = u.pn * BM + wc * 32 + 8 * fq;
; #pragma unroll
;       for (int ai = 0; ai < 2; ++ai)
; #pragma unroll
;         for (int m = 0; m < 4; ++m) { bf16_t* rowp = Z + (size_t)(row0 + ai * HALF + m * 16) * ZS + col0;
; #pragma unroll
;           for (int bj = 0; bj < 2; ++bj) *(u32x4*)(rowp + bj * HALF) = pack8v(acc[ai][bj][m][0], acc[ai][bj][m][1]); }
.LBB0_470:
	v_or_b32_e32 v20, s1, v142
	v_ashrrev_i32_e32 v21, 31, v20
	v_mov_b64_e32 v[22:23], s[88:89]
	v_mad_i64_i32 v[28:29], s[42:43], v138, s18, v[22:23]
	v_lshlrev_b64 v[20:21], 1, v[20:21]
	v_lshl_add_u64 v[28:29], v[28:29], 0, v[20:21]
	global_store_dwordx4 v[28:29], v[124:127], off nt
	global_store_dwordx4 v[28:29], v[104:107], off offset:256 nt
	v_or_b32_e32 v28, 16, v138
	v_mad_i64_i32 v[28:29], s[42:43], v28, s18, v[22:23]
	v_lshl_add_u64 v[28:29], v[28:29], 0, v[20:21]
	global_store_dwordx4 v[28:29], v[96:99], off nt
	global_store_dwordx4 v[28:29], v[88:91], off offset:256 nt
	v_or_b32_e32 v28, 32, v138
	v_mad_i64_i32 v[28:29], s[42:43], v28, s18, v[22:23]
	v_lshl_add_u64 v[28:29], v[28:29], 0, v[20:21]
	global_store_dwordx4 v[28:29], v[80:83], off nt
	global_store_dwordx4 v[28:29], v[76:79], off offset:256 nt
	v_or_b32_e32 v28, 48, v138
	v_mad_i64_i32 v[28:29], s[42:43], v28, s18, v[22:23]
	v_lshl_add_u64 v[28:29], v[28:29], 0, v[20:21]
	global_store_dwordx4 v[28:29], v[72:75], off nt
	global_store_dwordx4 v[28:29], v[68:71], off offset:256 nt
	v_add_u32_e32 v28, 0x80, v138
	v_mad_i64_i32 v[28:29], s[42:43], v28, s18, v[22:23]
	v_lshl_add_u64 v[28:29], v[28:29], 0, v[20:21]
	global_store_dwordx4 v[28:29], v[60:63], off nt
	global_store_dwordx4 v[28:29], v[40:43], off offset:256 nt
	v_add_u32_e32 v28, 0x90, v138
	v_mad_i64_i32 v[28:29], s[42:43], v28, s18, v[22:23]
	v_lshl_add_u64 v[28:29], v[28:29], 0, v[20:21]
	global_store_dwordx4 v[28:29], v[32:35], off nt
	global_store_dwordx4 v[28:29], v[24:27], off offset:256 nt
	s_nop 1
	v_add_u32_e32 v24, 0xa0, v138
	v_mad_i64_i32 v[24:25], s[42:43], v24, s18, v[22:23]
	v_lshl_add_u64 v[24:25], v[24:25], 0, v[20:21]
	global_store_dwordx4 v[24:25], v[16:19], off nt
	global_store_dwordx4 v[24:25], v[12:15], off offset:256 nt
	s_nop 1
	v_add_u32_e32 v12, 0xb0, v138
	v_mad_i64_i32 v[12:13], s[42:43], v12, s18, v[22:23]
	v_lshl_add_u64 v[20:21], v[12:13], 0, v[20:21]
	global_store_dwordx4 v[20:21], v[8:11], off nt
	s_branch .LBB0_456

; #define PG8_STAGE(bufoff, gbase, voff) do { _Pragma("unroll") for (int _i = 0; _i < 2; ++_i) \
;     __builtin_amdgcn_global_load_lds((const unsigned*)((const char*)(gbase) + (voff)[_i]), (LAS unsigned*)(lds + (bufoff) + ldsw + _i * 8192), 16, 0, 0); } while (0)
; #define PG8_LDA(dst, b, h) do { _Pragma("unroll") for (int m = 0; m < 4; ++m) _Pragma("unroll") for (int k = 0; k < 2; ++k) dst[m][k] = *(const LAS bf16x8*)(lds + PG8_SA(b, h) + aoff + m * 2048 + k * 1024); } while (0)
; #define PG8_LDB(dst, b, h) do { _Pragma("unroll") for (int n = 0; n < 2; ++n) _Pragma("unroll") for (int k = 0; k < 2; ++k) dst[n][k] = *(const LAS bf16x8*)(lds + PG8_SB(b, h) + boff + n * 2048 + k * 1024); } while (0)
; #define PG8_MMA(ai, bj, At, Bt_) do { __builtin_amdgcn_s_setprio(1); _Pragma("unroll") for (int m = 0; m < 4; ++m) _Pragma("unroll") for (int n = 0; n < 2; ++n) _Pragma("unroll") for (int k = 0; k < 2; ++k) \
;     acc[ai][bj][m][n] = __builtin_amdgcn_mfma_f32_16x16x32_bf16(Bt_[n][k], At[m][k], acc[ai][bj][m][n], 0, 0, 0); __builtin_amdgcn_s_setprio(0); } while (0)
; #define PG8_WAIT_V(n) asm volatile("s_waitcnt vmcnt(" #n ")" ::: "memory")
; #define PG8_WAIT_L(n) asm volatile("s_waitcnt lgkmcnt(" #n ")" ::: "memory")
; #define PG8_BAR __builtin_amdgcn_s_barrier()
; #define PG8_SCHED __builtin_amdgcn_sched_barrier(0)
; #define PG8_LDA(dst, b, h) do { _Pragma("unroll") for (int m = 0; m < 4; ++m) _Pragma("unroll") for (int k = 0; k < 2; ++k) dst[m][k] = *(const LAS bf16x8*)(lds + PG8_SA(b, h) + aoff + m * 2048 + k * 1024); } while (0)
; #define PG8_WAIT_V(n) asm volatile("s_waitcnt vmcnt(" #n ")" ::: "memory")
; template <class Epi>
; DI void gemm_phase(char* smem, const bf16_t* A, int lda, const bf16_t* Bt, int ldb, int K, const Order& S_, const Epi& E) {
;     ...
;       PG8_LDB(B0, 0, 0); PG8_SCHED; PG8_LDA(At, 0, 0); PG8_STAGE(PG8_SA(1, 1), a1 + hstepA, voffA);
;       PG8_WAIT_L(8); PG8_BAR; PG8_WAIT_L(0); PG8_MMA(0, 0, At, B0); PG8_BAR; PG8_SCHED;
;       PG8_LDB(B1, 0, 1); PG8_STAGE(PG8_SB(0, 0), b2, voffB);
;       PG8_BAR; PG8_WAIT_L(0); PG8_MMA(0, 1, At, B1); PG8_BAR;
;       PG8_LDA(At, 0, 1); PG8_STAGE(PG8_SA(0, 0), a2, voffA);
;       PG8_BAR; PG8_WAIT_L(0); PG8_MMA(1, 0, At, B0); PG8_BAR; PG8_SCHED;
;       PG8_STAGE(PG8_SB(0, 1), b2 + hstepB, voffB);
;       PG8_WAIT_V(6); PG8_BAR; PG8_MMA(1, 1, At, B1); PG8_BAR;
.LBB0_1858:
	s_add_u32 s42, vcc_lo, 0xfffc0080
	s_addc_u32 s43, vcc_hi, -1
	s_add_i32 s52, 0, 0x10000
	v_add_u32_e32 v154, s52, v139
	ds_read_b128 v[142:145], v154
	ds_read_b128 v[146:149], v154 offset:1024
	ds_read_b128 v[150:153], v154 offset:2048
	ds_read_b128 v[154:157], v154 offset:3072
	s_cmp_eq_u32 s41, 12
	s_cselect_b32 s89, s4, s43
	s_cselect_b32 s88, s5, s42
	s_cselect_b32 s43, s15, s29
	s_cselect_b32 s42, s16, s20
	v_lshl_add_u64 v[190:191], vcc, 0, v[134:135]
	s_add_i32 m0, s1, 0xc000
	ds_read_b128 v[158:161], v141
	ds_read_b128 v[162:165], v141 offset:1024
	ds_read_b128 v[166:169], v141 offset:2048
	ds_read_b128 v[170:173], v141 offset:3072
	ds_read_b128 v[174:177], v141 offset:4096
	ds_read_b128 v[178:181], v141 offset:5120
	ds_read_b128 v[182:185], v141 offset:6144
	ds_read_b128 v[186:189], v141 offset:7168
	global_load_lds_dwordx4 v[190:191], off
	v_lshl_add_u64 v[190:191], vcc, 0, v[136:137]
	s_add_i32 m0, s1, 0xe000
	s_nop 0
	global_load_lds_dwordx4 v[190:191], off
	s_waitcnt lgkmcnt(8)
	s_barrier
	s_waitcnt lgkmcnt(0)
	s_setprio 1
	s_waitcnt lgkmcnt(0)
	v_mfma_f32_16x16x32_bf16 v[124:127], v[142:145], v[158:161], v[124:127]
	v_mfma_f32_16x16x32_bf16 v[116:119], v[150:153], v[158:161], v[116:119]
	v_mfma_f32_16x16x32_bf16 v[108:111], v[142:145], v[166:169], v[108:111]
	v_mfma_f32_16x16x32_bf16 v[100:103], v[150:153], v[166:169], v[100:103]
	v_mfma_f32_16x16x32_bf16 v[92:95], v[142:145], v[174:177], v[92:95]
	v_mfma_f32_16x16x32_bf16 v[84:87], v[150:153], v[174:177], v[84:87]
	v_mfma_f32_16x16x32_bf16 v[76:79], v[142:145], v[182:185], v[76:79]
	v_mfma_f32_16x16x32_bf16 v[68:71], v[150:153], v[182:185], v[68:71]
	v_mfma_f32_16x16x32_bf16 v[124:127], v[146:149], v[162:165], v[124:127]
	v_mfma_f32_16x16x32_bf16 v[116:119], v[154:157], v[162:165], v[116:119]
	v_mfma_f32_16x16x32_bf16 v[108:111], v[146:149], v[170:173], v[108:111]
	v_mfma_f32_16x16x32_bf16 v[100:103], v[154:157], v[170:173], v[100:103]
	v_mfma_f32_16x16x32_bf16 v[92:95], v[146:149], v[178:181], v[92:95]
	v_mfma_f32_16x16x32_bf16 v[84:87], v[154:157], v[178:181], v[84:87]
	v_mfma_f32_16x16x32_bf16 v[76:79], v[146:149], v[186:189], v[76:79]
	v_mfma_f32_16x16x32_bf16 v[68:71], v[154:157], v[186:189], v[68:71]
	s_setprio 0
	s_barrier
	s_add_i32 s56, 0, 0x14000
	v_add_u32_e32 v190, s56, v139
	s_add_i32 s52, s52, s33
	ds_read_b128 v[210:213], v190
	ds_read_b128 v[214:217], v190 offset:1024
	ds_read_b128 v[234:237], v190 offset:2048
	ds_read_b128 v[238:241], v190 offset:3072
	v_lshl_add_u64 v[190:191], s[42:43], 0, v[220:221]
	s_mov_b32 m0, s52
	v_lshl_add_u64 v[194:195], s[42:43], 0, v[132:133]
	global_load_lds_dwordx4 v[190:191], off
	s_add_i32 m0, s52, 0x2000
	s_nop 0
	global_load_lds_dwordx4 v[194:195], off
	s_barrier
	s_waitcnt lgkmcnt(0)
	s_setprio 1
	s_waitcnt lgkmcnt(0)
	v_mfma_f32_16x16x32_bf16 v[120:123], v[210:213], v[158:161], v[120:123]
	v_mfma_f32_16x16x32_bf16 v[112:115], v[234:237], v[158:161], v[112:115]
	v_mfma_f32_16x16x32_bf16 v[104:107], v[210:213], v[166:169], v[104:107]
	v_mfma_f32_16x16x32_bf16 v[96:99], v[234:237], v[166:169], v[96:99]
	v_mfma_f32_16x16x32_bf16 v[88:91], v[210:213], v[174:177], v[88:91]
	v_mfma_f32_16x16x32_bf16 v[80:83], v[234:237], v[174:177], v[80:83]
	v_mfma_f32_16x16x32_bf16 v[72:75], v[210:213], v[182:185], v[72:75]
	v_mfma_f32_16x16x32_bf16 v[64:67], v[234:237], v[182:185], v[64:67]
	v_mfma_f32_16x16x32_bf16 v[120:123], v[214:217], v[162:165], v[120:123]
	v_mfma_f32_16x16x32_bf16 v[112:115], v[238:241], v[162:165], v[112:115]
	v_mfma_f32_16x16x32_bf16 v[104:107], v[214:217], v[170:173], v[104:107]
	v_mfma_f32_16x16x32_bf16 v[96:99], v[238:241], v[170:173], v[96:99]
	v_mfma_f32_16x16x32_bf16 v[88:91], v[214:217], v[178:181], v[88:91]
	v_mfma_f32_16x16x32_bf16 v[80:83], v[238:241], v[178:181], v[80:83]
	v_mfma_f32_16x16x32_bf16 v[72:75], v[214:217], v[186:189], v[72:75]
	v_mfma_f32_16x16x32_bf16 v[64:67], v[238:241], v[186:189], v[64:67]
	s_setprio 0
	s_mov_b32 m0, s1
	v_lshl_add_u64 v[200:201], s[88:89], 0, v[128:129]
	s_barrier
	ds_read_b128 v[158:161], v141 offset:16384
	ds_read_b128 v[162:165], v141 offset:17408
	ds_read_b128 v[166:169], v141 offset:18432
	ds_read_b128 v[170:173], v141 offset:19456
	ds_read_b128 v[174:177], v141 offset:20480
	ds_read_b128 v[178:181], v141 offset:21504
	ds_read_b128 v[182:185], v141 offset:22528
	ds_read_b128 v[186:189], v141 offset:23552
	global_load_lds_dwordx4 v[200:201], off
	v_lshl_add_u64 v[202:203], s[88:89], 0, v[130:131]
	s_mov_b32 m0, s34
	s_nop 0
	global_load_lds_dwordx4 v[202:203], off
	s_barrier
	s_waitcnt lgkmcnt(0)
	s_setprio 1
	s_waitcnt lgkmcnt(0)
	v_mfma_f32_16x16x32_bf16 v[60:63], v[142:145], v[158:161], v[60:63]
	v_mfma_f32_16x16x32_bf16 v[52:55], v[150:153], v[158:161], v[52:55]
	v_mfma_f32_16x16x32_bf16 v[44:47], v[142:145], v[166:169], v[44:47]
	v_mfma_f32_16x16x32_bf16 v[36:39], v[150:153], v[166:169], v[36:39]
	v_mfma_f32_16x16x32_bf16 v[28:31], v[142:145], v[174:177], v[28:31]
	v_mfma_f32_16x16x32_bf16 v[20:23], v[150:153], v[174:177], v[20:23]
	v_mfma_f32_16x16x32_bf16 v[12:15], v[142:145], v[182:185], v[12:15]
	v_mfma_f32_16x16x32_bf16 v[4:7], v[150:153], v[182:185], v[4:7]
	v_mfma_f32_16x16x32_bf16 v[60:63], v[146:149], v[162:165], v[60:63]
	v_mfma_f32_16x16x32_bf16 v[52:55], v[154:157], v[162:165], v[52:55]
	v_mfma_f32_16x16x32_bf16 v[44:47], v[146:149], v[170:173], v[44:47]
	v_mfma_f32_16x16x32_bf16 v[36:39], v[154:157], v[170:173], v[36:39]
	v_mfma_f32_16x16x32_bf16 v[28:31], v[146:149], v[178:181], v[28:31]
	v_mfma_f32_16x16x32_bf16 v[20:23], v[154:157], v[178:181], v[20:23]
	v_mfma_f32_16x16x32_bf16 v[12:15], v[146:149], v[186:189], v[12:15]
	v_mfma_f32_16x16x32_bf16 v[4:7], v[154:157], v[186:189], v[4:7]
	s_setprio 0
	s_barrier
; #define PG8_STAGE(bufoff, gbase, voff) do { _Pragma("unroll") for (int _i = 0; _i < 2; ++_i) \
;     __builtin_amdgcn_global_load_lds((const unsigned*)((const char*)(gbase) + (voff)[_i]), (LAS unsigned*)(lds + (bufoff) + ldsw + _i * 8192), 16, 0, 0); } while (0)
; #define PG8_LDA(dst, b, h) do { _Pragma("unroll") for (int m = 0; m < 4; ++m) _Pragma("unroll") for (int k = 0; k < 2; ++k) dst[m][k] = *(const LAS bf16x8*)(lds + PG8_SA(b, h) + aoff + m * 2048 + k * 1024); } while (0)
; #define PG8_LDB(dst, b, h) do { _Pragma("unroll") for (int n = 0; n < 2; ++n) _Pragma("unroll") for (int k = 0; k < 2; ++k) dst[n][k] = *(const LAS bf16x8*)(lds + PG8_SB(b, h) + boff + n * 2048 + k * 1024); } while (0)
; #define PG8_MMA(ai, bj, At, Bt_) do { __builtin_amdgcn_s_setprio(1); _Pragma("unroll") for (int m = 0; m < 4; ++m) _Pragma("unroll") for (int n = 0; n < 2; ++n) _Pragma("unroll") for (int k = 0; k < 2; ++k) \
;     acc[ai][bj][m][n] = __builtin_amdgcn_mfma_f32_16x16x32_bf16(Bt_[n][k], At[m][k], acc[ai][bj][m][n], 0, 0, 0); __builtin_amdgcn_s_setprio(0); } while (0)
; #define PG8_WAIT_V(n) asm volatile("s_waitcnt vmcnt(" #n ")" ::: "memory")
; #define PG8_WAIT_L(n) asm volatile("s_waitcnt lgkmcnt(" #n ")" ::: "memory")
; #define PG8_BAR __builtin_amdgcn_s_barrier()
; #define PG8_SCHED __builtin_amdgcn_sched_barrier(0)
; #define PG8_LDA(dst, b, h) do { _Pragma("unroll") for (int m = 0; m < 4; ++m) _Pragma("unroll") for (int k = 0; k < 2; ++k) dst[m][k] = *(const LAS bf16x8*)(lds + PG8_SA(b, h) + aoff + m * 2048 + k * 1024); } while (0)
; #define PG8_WAIT_V(n) asm volatile("s_waitcnt vmcnt(" #n ")" ::: "memory")
; #define PG8_WAIT_L(n) asm volatile("s_waitcnt lgkmcnt(" #n ")" ::: "memory")
; template <class Epi>
; DI void gemm_phase(char* smem, const bf16_t* A, int lda, const bf16_t* Bt, int ldb, int K, const Order& S_, const Epi& E) {
;     ...
;       PG8_STAGE(PG8_SB(0, 1), b2 + hstepB, voffB);
;       PG8_WAIT_V(6); PG8_BAR; PG8_MMA(1, 1, At, B1); PG8_BAR;
;       PG8_LDB(B0, 1, 0); PG8_SCHED; PG8_LDA(At, 1, 0); PG8_STAGE(PG8_SA(0, 1), a2 + hstepA, voffA);
;       PG8_WAIT_L(8); PG8_BAR; PG8_WAIT_L(0); PG8_MMA(0, 0, At, B0); PG8_BAR; PG8_SCHED;
;       PG8_LDB(B1, 1, 1); PG8_STAGE(PG8_SB(1, 0), b3, voffB);
;       PG8_BAR; PG8_WAIT_L(0); PG8_MMA(0, 1, At, B1); PG8_BAR;
;       PG8_LDA(At, 1, 1); PG8_STAGE(PG8_SA(1, 0), a3, voffA);
	s_add_u32 s52, s42, 0x40000
	s_addc_u32 s53, s43, 0
	s_add_i32 s56, s56, s33
	v_lshl_add_u64 v[142:143], s[52:53], 0, v[220:221]
	s_mov_b32 m0, s56
	s_nop 0
	global_load_lds_dwordx4 v[142:143], off
	v_lshl_add_u64 v[142:143], s[52:53], 0, v[132:133]
	s_add_i32 m0, s56, 0x2000
	s_nop 0
	global_load_lds_dwordx4 v[142:143], off
	s_waitcnt vmcnt(6)
	s_barrier
	s_setprio 1
	v_mfma_f32_16x16x32_bf16 v[56:59], v[210:213], v[158:161], v[56:59]
	v_mfma_f32_16x16x32_bf16 v[48:51], v[234:237], v[158:161], v[48:51]
	v_mfma_f32_16x16x32_bf16 v[40:43], v[210:213], v[166:169], v[40:43]
	v_mfma_f32_16x16x32_bf16 v[32:35], v[234:237], v[166:169], v[32:35]
	v_mfma_f32_16x16x32_bf16 v[24:27], v[210:213], v[174:177], v[24:27]
	v_mfma_f32_16x16x32_bf16 v[16:19], v[234:237], v[174:177], v[16:19]
	v_mfma_f32_16x16x32_bf16 v[8:11], v[210:213], v[182:185], v[8:11]
	v_mfma_f32_16x16x32_bf16 v[0:3], v[234:237], v[182:185], v[0:3]
	v_mfma_f32_16x16x32_bf16 v[56:59], v[214:217], v[162:165], v[56:59]
	v_mfma_f32_16x16x32_bf16 v[48:51], v[238:241], v[162:165], v[48:51]
	v_mfma_f32_16x16x32_bf16 v[40:43], v[214:217], v[170:173], v[40:43]
	v_mfma_f32_16x16x32_bf16 v[32:35], v[238:241], v[170:173], v[32:35]
	v_mfma_f32_16x16x32_bf16 v[24:27], v[214:217], v[178:181], v[24:27]
	v_mfma_f32_16x16x32_bf16 v[16:19], v[238:241], v[178:181], v[16:19]
	v_mfma_f32_16x16x32_bf16 v[8:11], v[214:217], v[186:189], v[8:11]
	v_mfma_f32_16x16x32_bf16 v[0:3], v[238:241], v[186:189], v[0:3]
	s_setprio 0
	s_add_i32 s56, 0, 0x18000
	v_add_u32_e32 v154, s56, v139
	s_barrier
	ds_read_b128 v[142:145], v154
	ds_read_b128 v[146:149], v154 offset:1024
	ds_read_b128 v[150:153], v154 offset:2048
	ds_read_b128 v[154:157], v154 offset:3072
	s_add_u32 s52, s88, 0x40000
	s_addc_u32 s53, s89, 0
	s_mov_b32 m0, s38
	v_lshl_add_u64 v[208:209], s[52:53], 0, v[128:129]
	ds_read_b128 v[158:161], v141 offset:32768
	ds_read_b128 v[162:165], v141 offset:33792
	ds_read_b128 v[166:169], v141 offset:34816
	ds_read_b128 v[170:173], v141 offset:35840
	ds_read_b128 v[174:177], v141 offset:36864
	ds_read_b128 v[178:181], v141 offset:37888
	ds_read_b128 v[182:185], v141 offset:38912
	ds_read_b128 v[186:189], v141 offset:39936
	global_load_lds_dwordx4 v[208:209], off
	v_lshl_add_u64 v[208:209], s[52:53], 0, v[130:131]
	s_mov_b32 m0, s39
	s_nop 0
	global_load_lds_dwordx4 v[208:209], off
	s_waitcnt lgkmcnt(8)
	s_barrier
	s_waitcnt lgkmcnt(0)
	s_setprio 1
	s_waitcnt lgkmcnt(0)
	v_mfma_f32_16x16x32_bf16 v[124:127], v[142:145], v[158:161], v[124:127]
	v_mfma_f32_16x16x32_bf16 v[116:119], v[150:153], v[158:161], v[116:119]
	v_mfma_f32_16x16x32_bf16 v[108:111], v[142:145], v[166:169], v[108:111]
	v_mfma_f32_16x16x32_bf16 v[100:103], v[150:153], v[166:169], v[100:103]
	v_mfma_f32_16x16x32_bf16 v[92:95], v[142:145], v[174:177], v[92:95]
	v_mfma_f32_16x16x32_bf16 v[84:87], v[150:153], v[174:177], v[84:87]
	v_mfma_f32_16x16x32_bf16 v[76:79], v[142:145], v[182:185], v[76:79]
	v_mfma_f32_16x16x32_bf16 v[68:71], v[150:153], v[182:185], v[68:71]
	v_mfma_f32_16x16x32_bf16 v[124:127], v[146:149], v[162:165], v[124:127]
	v_mfma_f32_16x16x32_bf16 v[116:119], v[154:157], v[162:165], v[116:119]
	v_mfma_f32_16x16x32_bf16 v[108:111], v[146:149], v[170:173], v[108:111]
	v_mfma_f32_16x16x32_bf16 v[100:103], v[154:157], v[170:173], v[100:103]
	v_mfma_f32_16x16x32_bf16 v[92:95], v[146:149], v[178:181], v[92:95]
	v_mfma_f32_16x16x32_bf16 v[84:87], v[154:157], v[178:181], v[84:87]
	v_mfma_f32_16x16x32_bf16 v[76:79], v[146:149], v[186:189], v[76:79]
	v_mfma_f32_16x16x32_bf16 v[68:71], v[154:157], v[186:189], v[68:71]
	s_setprio 0
	s_barrier
	s_add_i32 s52, 0, 0x1c000
	s_add_i32 s53, s56, s33
	v_add_u32_e32 v204, s52, v139
	v_lshl_add_u64 v[190:191], v[190:191], 0, s[58:59]
	s_mov_b32 m0, s53
	ds_read_b128 v[210:213], v204
	ds_read_b128 v[214:217], v204 offset:1024
	ds_read_b128 v[234:237], v204 offset:2048
	ds_read_b128 v[238:241], v204 offset:3072
	global_load_lds_dwordx4 v[190:191], off
	v_lshl_add_u64 v[190:191], v[194:195], 0, s[58:59]
	s_add_i32 m0, s53, 0x2000
	s_nop 0
	global_load_lds_dwordx4 v[190:191], off
	s_barrier
	s_waitcnt lgkmcnt(0)
	s_setprio 1
	s_waitcnt lgkmcnt(0)
	v_mfma_f32_16x16x32_bf16 v[120:123], v[210:213], v[158:161], v[120:123]
	v_mfma_f32_16x16x32_bf16 v[112:115], v[234:237], v[158:161], v[112:115]
	v_mfma_f32_16x16x32_bf16 v[104:107], v[210:213], v[166:169], v[104:107]
	v_mfma_f32_16x16x32_bf16 v[96:99], v[234:237], v[166:169], v[96:99]
	v_mfma_f32_16x16x32_bf16 v[88:91], v[210:213], v[174:177], v[88:91]
	v_mfma_f32_16x16x32_bf16 v[80:83], v[234:237], v[174:177], v[80:83]
	v_mfma_f32_16x16x32_bf16 v[72:75], v[210:213], v[182:185], v[72:75]
	v_mfma_f32_16x16x32_bf16 v[64:67], v[234:237], v[182:185], v[64:67]
	v_mfma_f32_16x16x32_bf16 v[120:123], v[214:217], v[162:165], v[120:123]
	v_mfma_f32_16x16x32_bf16 v[112:115], v[238:241], v[162:165], v[112:115]
	v_mfma_f32_16x16x32_bf16 v[104:107], v[214:217], v[170:173], v[104:107]
	v_mfma_f32_16x16x32_bf16 v[96:99], v[238:241], v[170:173], v[96:99]
	v_mfma_f32_16x16x32_bf16 v[88:91], v[214:217], v[178:181], v[88:91]
	v_mfma_f32_16x16x32_bf16 v[80:83], v[238:241], v[178:181], v[80:83]
	v_mfma_f32_16x16x32_bf16 v[72:75], v[214:217], v[186:189], v[72:75]
	v_mfma_f32_16x16x32_bf16 v[64:67], v[238:241], v[186:189], v[64:67]
	s_setprio 0
	s_mov_b32 m0, s47
	v_lshl_add_u64 v[190:191], v[200:201], 0, s[58:59]
	s_barrier
	ds_read_b128 v[158:161], v141 offset:49152
	ds_read_b128 v[162:165], v141 offset:50176
	ds_read_b128 v[166:169], v141 offset:51200
	ds_read_b128 v[170:173], v141 offset:52224
	ds_read_b128 v[174:177], v141 offset:53248
	ds_read_b128 v[178:181], v141 offset:54272
	ds_read_b128 v[182:185], v141 offset:55296
	ds_read_b128 v[186:189], v141 offset:56320
	global_load_lds_dwordx4 v[190:191], off
	v_lshl_add_u64 v[190:191], v[202:203], 0, s[58:59]
	s_mov_b32 m0, s49
	s_nop 0
	global_load_lds_dwordx4 v[190:191], off
	s_barrier
; DI float siluf_(float x) { return x * sigmoidf_(x); }
; #define PG8_STAGE(bufoff, gbase, voff) do { _Pragma("unroll") for (int _i = 0; _i < 2; ++_i) \
;     __builtin_amdgcn_global_load_lds((const unsigned*)((const char*)(gbase) + (voff)[_i]), (LAS unsigned*)(lds + (bufoff) + ldsw + _i * 8192), 16, 0, 0); } while (0)
; #define PG8_MMA(ai, bj, At, Bt_) do { __builtin_amdgcn_s_setprio(1); _Pragma("unroll") for (int m = 0; m < 4; ++m) _Pragma("unroll") for (int n = 0; n < 2; ++n) _Pragma("unroll") for (int k = 0; k < 2; ++k) \
;     acc[ai][bj][m][n] = __builtin_amdgcn_mfma_f32_16x16x32_bf16(Bt_[n][k], At[m][k], acc[ai][bj][m][n], 0, 0, 0); __builtin_amdgcn_s_setprio(0); } while (0)
; #define PG8_WAIT_V(n) asm volatile("s_waitcnt vmcnt(" #n ")" ::: "memory")
; #define PG8_WAIT_L(n) asm volatile("s_waitcnt lgkmcnt(" #n ")" ::: "memory")
; #define PG8_BAR __builtin_amdgcn_s_barrier()
; #define PG8_SCHED __builtin_amdgcn_sched_barrier(0)
; DI u32x4 pack8v(const f32x4& a, const f32x4& b) { u32x4 w; w.x = pk2(a[0], a[1]); w.y = pk2(a[2], a[3]); w.z = pk2(b[0], b[1]); w.w = pk2(b[2], b[3]); return w; }
; #define PG8_WAIT_V(n) asm volatile("s_waitcnt vmcnt(" #n ")" ::: "memory")
; #define PG8_WAIT_L(n) asm volatile("s_waitcnt lgkmcnt(" #n ")" ::: "memory")
; #define PG8_BAR __builtin_amdgcn_s_barrier()
; #define PG8_SCHED __builtin_amdgcn_sched_barrier(0)
; template <class Epi>
; DI void gemm_phase(char* smem, const bf16_t* A, int lda, const bf16_t* Bt, int ldb, int K, const Order& S_, const Epi& E) {
;     ...
;       PG8_BAR; PG8_WAIT_L(0); PG8_MMA(1, 0, At, B0); PG8_BAR; PG8_SCHED;
;       PG8_STAGE(PG8_SB(1, 1), b3 + hstepB, voffB);
;       PG8_WAIT_V(6); PG8_BAR; PG8_MMA(1, 1, At, B1); PG8_BAR;
;   DI void operator()(const acc_t& acc, const Unit& u, int wr, int wc, int fr, int fq) const {
;     const int row0 = u.pm * BM + wr * 64 + fr, col0 = u.pn * HALF + wc * 32 + 8 * fq;
; #pragma unroll
;     for (int ai = 0; ai < 2; ++ai)
; #pragma unroll
;       for (int m = 0; m < 4; ++m) {
;         f32x4 r0, r1;
; #pragma unroll
;         for (int e = 0; e < 4; ++e) { r0[e] = siluf_(acc[ai][0][m][0][e]) * acc[ai][1][m][0][e]; r1[e] = siluf_(acc[ai][0][m][1][e]) * acc[ai][1][m][1][e]; }
;         *(u32x4*)(G + (size_t)(row0 + ai * HALF + m * 16) * DFF + col0) = pack8v(r0, r1); }
	s_waitcnt lgkmcnt(0)
	s_setprio 1
	s_waitcnt lgkmcnt(0)
	v_mfma_f32_16x16x32_bf16 v[60:63], v[142:145], v[158:161], v[60:63]
	v_mfma_f32_16x16x32_bf16 v[52:55], v[150:153], v[158:161], v[52:55]
	v_mfma_f32_16x16x32_bf16 v[44:47], v[142:145], v[166:169], v[44:47]
	v_mfma_f32_16x16x32_bf16 v[36:39], v[150:153], v[166:169], v[36:39]
	v_mfma_f32_16x16x32_bf16 v[28:31], v[142:145], v[174:177], v[28:31]
	v_mfma_f32_16x16x32_bf16 v[20:23], v[150:153], v[174:177], v[20:23]
	v_mfma_f32_16x16x32_bf16 v[12:15], v[142:145], v[182:185], v[12:15]
	v_mfma_f32_16x16x32_bf16 v[4:7], v[150:153], v[182:185], v[4:7]
	v_mfma_f32_16x16x32_bf16 v[60:63], v[146:149], v[162:165], v[60:63]
	v_mfma_f32_16x16x32_bf16 v[52:55], v[154:157], v[162:165], v[52:55]
	v_mfma_f32_16x16x32_bf16 v[44:47], v[146:149], v[170:173], v[44:47]
	v_mfma_f32_16x16x32_bf16 v[36:39], v[154:157], v[170:173], v[36:39]
	v_mfma_f32_16x16x32_bf16 v[28:31], v[146:149], v[178:181], v[28:31]
	v_mfma_f32_16x16x32_bf16 v[20:23], v[154:157], v[178:181], v[20:23]
	v_mfma_f32_16x16x32_bf16 v[12:15], v[146:149], v[186:189], v[12:15]
	v_mfma_f32_16x16x32_bf16 v[4:7], v[154:157], v[186:189], v[4:7]
	s_setprio 0
	s_barrier
	s_add_u32 s42, s42, 0x40080
	s_addc_u32 s43, s43, 0
	s_add_i32 s52, s52, s33
	v_lshl_add_u64 v[142:143], s[42:43], 0, v[220:221]
	s_mov_b32 m0, s52
	s_nop 0
	global_load_lds_dwordx4 v[142:143], off
	v_lshl_add_u64 v[142:143], s[42:43], 0, v[132:133]
	s_add_i32 m0, s52, 0x2000
	s_nop 0
	global_load_lds_dwordx4 v[142:143], off
	s_waitcnt vmcnt(6)
	s_barrier
	s_setprio 1
	v_mfma_f32_16x16x32_bf16 v[56:59], v[210:213], v[158:161], v[56:59]
	v_mfma_f32_16x16x32_bf16 v[48:51], v[234:237], v[158:161], v[48:51]
	v_mfma_f32_16x16x32_bf16 v[40:43], v[210:213], v[166:169], v[40:43]
	v_mfma_f32_16x16x32_bf16 v[32:35], v[234:237], v[166:169], v[32:35]
	v_mfma_f32_16x16x32_bf16 v[24:27], v[210:213], v[174:177], v[24:27]
	v_mfma_f32_16x16x32_bf16 v[16:19], v[234:237], v[174:177], v[16:19]
	v_mfma_f32_16x16x32_bf16 v[8:11], v[210:213], v[182:185], v[8:11]
	v_mfma_f32_16x16x32_bf16 v[0:3], v[234:237], v[182:185], v[0:3]
	v_mfma_f32_16x16x32_bf16 v[56:59], v[214:217], v[162:165], v[56:59]
	v_mfma_f32_16x16x32_bf16 v[48:51], v[238:241], v[162:165], v[48:51]
	v_mfma_f32_16x16x32_bf16 v[40:43], v[214:217], v[170:173], v[40:43]
	v_mfma_f32_16x16x32_bf16 v[32:35], v[238:241], v[170:173], v[32:35]
	v_mfma_f32_16x16x32_bf16 v[24:27], v[214:217], v[178:181], v[24:27]
	v_mfma_f32_16x16x32_bf16 v[16:19], v[238:241], v[178:181], v[16:19]
	v_mfma_f32_16x16x32_bf16 v[8:11], v[214:217], v[186:189], v[8:11]
	v_mfma_f32_16x16x32_bf16 v[0:3], v[238:241], v[186:189], v[0:3]
	s_setprio 0
	s_add_i32 s41, s41, 2
	s_add_u32 vcc_lo, vcc_lo, 0x100
	s_addc_u32 vcc_hi, vcc_hi, 0
	s_add_u32 s20, s20, 0x100
	s_addc_u32 s29, s29, 0
	s_cmp_gt_u32 s41, 13
	s_barrier
	s_cbranch_scc0 .LBB0_1858
	v_mul_f32_e32 v143, 0xbfb8aa3b, v124
	v_exp_f32_e32 v143, v143
	v_readlane_b32 s4, v254, 43
	v_lshl_or_b32 v144, s0, 7, v140
	v_readlane_b32 s5, v254, 44
	v_add_f32_e32 v143, 1.0, v143
	v_rcp_f32_e32 v146, v143
	v_mul_f32_e32 v143, 0xbfb8aa3b, v116
	v_exp_f32_e32 v143, v143
	v_lshl_add_u32 v142, s46, 8, v138
	v_ashrrev_i32_e32 v145, 31, v144
	s_and_b64 vcc, exec, s[36:37]
	v_add_f32_e32 v143, 1.0, v143
	v_rcp_f32_e32 v148, v143
	v_mul_f32_e32 v143, 0xbfb8aa3b, v125
	v_exp_f32_e32 v143, v143
	s_mov_b32 s0, s90
	s_mov_b32 s46, s40
	s_mov_b64 s[88:89], s[44:45]
	v_add_f32_e32 v143, 1.0, v143
	v_rcp_f32_e32 v147, v143
	s_mov_b64 s[42:43], s[50:51]
	s_mov_b32 s51, 0x78787879
	v_pk_mul_f32 v[124:125], v[124:125], v[146:147]
	s_nop 0
	v_pk_mul_f32 v[120:121], v[124:125], v[120:121]
	v_mul_f32_e32 v124, 0xbfb8aa3b, v117
	v_exp_f32_e32 v124, v124
	s_nop 0
	v_add_f32_e32 v124, 1.0, v124
	v_rcp_f32_e32 v149, v124
	s_nop 0
	v_pk_mul_f32 v[116:117], v[116:117], v[148:149]
	s_nop 0
	v_pk_mul_f32 v[112:113], v[116:117], v[112:113]
	v_mul_f32_e32 v117, 0xbfb8aa3b, v118
	v_exp_f32_e32 v117, v117
	v_mul_f32_e32 v116, 0xbfb8aa3b, v126
	v_exp_f32_e32 v116, v116
	v_add_f32_e32 v117, 1.0, v117
	v_rcp_f32_e32 v124, v117
	v_mul_f32_e32 v117, 0xbfb8aa3b, v127
	v_exp_f32_e32 v117, v117
	v_add_f32_e32 v116, 1.0, v116
	v_rcp_f32_e32 v116, v116
	v_add_f32_e32 v117, 1.0, v117
	v_rcp_f32_e32 v117, v117
	s_nop 0
	v_pk_mul_f32 v[116:117], v[126:127], v[116:117]
	s_nop 0
	v_pk_mul_f32 v[122:123], v[116:117], v[122:123]
	v_mul_f32_e32 v116, 0xbfb8aa3b, v119
	v_exp_f32_e32 v116, v116
	s_nop 0
	v_add_f32_e32 v116, 1.0, v116
	v_rcp_f32_e32 v125, v116
	s_nop 0
	v_pk_mul_f32 v[116:117], v[118:119], v[124:125]
	s_nop 0
	v_pk_mul_f32 v[114:115], v[116:117], v[114:115]
	v_cvt_pk_bf16_f32 v118, v112, v113
	v_mov_b64_e32 v[112:113], s[4:5]
	v_cvt_pk_bf16_f32 v116, v120, v121
	v_cvt_pk_bf16_f32 v119, v114, v115
	v_mad_i64_i32 v[120:121], s[4:5], v142, s18, v[112:113]
	v_lshlrev_b64 v[114:115], 1, v[144:145]
	v_cvt_pk_bf16_f32 v117, v122, v123
	v_lshl_add_u64 v[120:121], v[120:121], 0, v[114:115]
	global_store_dwordx4 v[120:121], v[116:119], off nt
	s_nop 1
	v_mul_f32_e32 v117, 0xbfb8aa3b, v100
	v_exp_f32_e32 v117, v117
	v_mul_f32_e32 v116, 0xbfb8aa3b, v108
	v_exp_f32_e32 v116, v116
	v_add_f32_e32 v117, 1.0, v117
	v_rcp_f32_e32 v118, v117
	v_mul_f32_e32 v117, 0xbfb8aa3b, v109
	v_exp_f32_e32 v117, v117
	v_add_f32_e32 v116, 1.0, v116
	v_rcp_f32_e32 v116, v116
	v_add_f32_e32 v117, 1.0, v117
	v_rcp_f32_e32 v117, v117
	s_nop 0
	v_pk_mul_f32 v[108:109], v[108:109], v[116:117]
	s_nop 0
	v_pk_mul_f32 v[104:105], v[108:109], v[104:105]
	v_mul_f32_e32 v108, 0xbfb8aa3b, v101
	v_exp_f32_e32 v108, v108
	s_nop 0
	v_add_f32_e32 v108, 1.0, v108
	v_rcp_f32_e32 v119, v108
	s_nop 0
; DI float siluf_(float x) { return x * sigmoidf_(x); }
; DI u32x4 pack8v(const f32x4& a, const f32x4& b) { u32x4 w; w.x = pk2(a[0], a[1]); w.y = pk2(a[2], a[3]); w.z = pk2(b[0], b[1]); w.w = pk2(b[2], b[3]); return w; }
;   DI void operator()(const acc_t& acc, const Unit& u, int wr, int wc, int fr, int fq) const {
;     ...
;     for (int ai = 0; ai < 2; ++ai)
; #pragma unroll
;       for (int m = 0; m < 4; ++m) {
;         f32x4 r0, r1;
; #pragma unroll
;         for (int e = 0; e < 4; ++e) { r0[e] = siluf_(acc[ai][0][m][0][e]) * acc[ai][1][m][0][e]; r1[e] = siluf_(acc[ai][0][m][1][e]) * acc[ai][1][m][1][e]; }
;         *(u32x4*)(G + (size_t)(row0 + ai * HALF + m * 16) * DFF + col0) = pack8v(r0, r1); }
	v_pk_mul_f32 v[100:101], v[100:101], v[118:119]
	s_nop 0
	v_pk_mul_f32 v[100:101], v[100:101], v[96:97]
	v_mul_f32_e32 v97, 0xbfb8aa3b, v102
	v_exp_f32_e32 v97, v97
	v_mul_f32_e32 v96, 0xbfb8aa3b, v110
	v_exp_f32_e32 v96, v96
	v_add_f32_e32 v97, 1.0, v97
	v_rcp_f32_e32 v108, v97
	v_mul_f32_e32 v97, 0xbfb8aa3b, v111
	v_exp_f32_e32 v97, v97
	v_add_f32_e32 v96, 1.0, v96
	v_rcp_f32_e32 v96, v96
	v_add_f32_e32 v97, 1.0, v97
	v_rcp_f32_e32 v97, v97
	s_nop 0
	v_pk_mul_f32 v[96:97], v[110:111], v[96:97]
	s_nop 0
	v_pk_mul_f32 v[106:107], v[96:97], v[106:107]
	v_mul_f32_e32 v96, 0xbfb8aa3b, v103
	v_exp_f32_e32 v96, v96
	s_nop 0
	v_add_f32_e32 v96, 1.0, v96
	v_rcp_f32_e32 v109, v96
	s_nop 0
	v_pk_mul_f32 v[96:97], v[102:103], v[108:109]
	s_nop 0
	v_pk_mul_f32 v[102:103], v[96:97], v[98:99]
	v_cvt_pk_bf16_f32 v98, v100, v101
	v_or_b32_e32 v100, 16, v142
	v_mad_i64_i32 v[100:101], s[4:5], v100, s18, v[112:113]
	v_cvt_pk_bf16_f32 v96, v104, v105
	v_cvt_pk_bf16_f32 v97, v106, v107
	v_cvt_pk_bf16_f32 v99, v102, v103
	v_lshl_add_u64 v[100:101], v[100:101], 0, v[114:115]
	global_store_dwordx4 v[100:101], v[96:99], off nt
	s_nop 1
	v_mul_f32_e32 v97, 0xbfb8aa3b, v84
	v_exp_f32_e32 v97, v97
	v_mul_f32_e32 v96, 0xbfb8aa3b, v92
	v_exp_f32_e32 v96, v96
	v_add_f32_e32 v97, 1.0, v97
	v_rcp_f32_e32 v98, v97
	v_mul_f32_e32 v97, 0xbfb8aa3b, v93
	v_exp_f32_e32 v97, v97
	v_add_f32_e32 v96, 1.0, v96
	v_rcp_f32_e32 v96, v96
	v_add_f32_e32 v97, 1.0, v97
	v_rcp_f32_e32 v97, v97
	s_nop 0
	v_pk_mul_f32 v[92:93], v[92:93], v[96:97]
	s_nop 0
	v_pk_mul_f32 v[88:89], v[92:93], v[88:89]
	v_mul_f32_e32 v92, 0xbfb8aa3b, v85
	v_exp_f32_e32 v92, v92
	s_nop 0
	v_add_f32_e32 v92, 1.0, v92
	v_rcp_f32_e32 v99, v92
	s_nop 0
	v_pk_mul_f32 v[84:85], v[84:85], v[98:99]
	s_nop 0
	v_pk_mul_f32 v[84:85], v[84:85], v[80:81]
	v_mul_f32_e32 v81, 0xbfb8aa3b, v86
	v_exp_f32_e32 v81, v81
	v_mul_f32_e32 v80, 0xbfb8aa3b, v94
	v_exp_f32_e32 v80, v80
	v_add_f32_e32 v81, 1.0, v81
	v_rcp_f32_e32 v92, v81
	v_mul_f32_e32 v81, 0xbfb8aa3b, v95
	v_exp_f32_e32 v81, v81
	v_add_f32_e32 v80, 1.0, v80
	v_rcp_f32_e32 v80, v80
	v_add_f32_e32 v81, 1.0, v81
	v_rcp_f32_e32 v81, v81
	s_nop 0
	v_pk_mul_f32 v[80:81], v[94:95], v[80:81]
	s_nop 0
	v_pk_mul_f32 v[90:91], v[80:81], v[90:91]
	v_mul_f32_e32 v80, 0xbfb8aa3b, v87
	v_exp_f32_e32 v80, v80
	s_nop 0
	v_add_f32_e32 v80, 1.0, v80
	v_rcp_f32_e32 v93, v80
	s_nop 0
	v_pk_mul_f32 v[80:81], v[86:87], v[92:93]
	s_nop 0
	v_pk_mul_f32 v[86:87], v[80:81], v[82:83]
	v_cvt_pk_bf16_f32 v82, v84, v85
	v_or_b32_e32 v84, 32, v142
	v_mad_i64_i32 v[84:85], s[4:5], v84, s18, v[112:113]
	v_cvt_pk_bf16_f32 v80, v88, v89
	v_cvt_pk_bf16_f32 v81, v90, v91
	v_cvt_pk_bf16_f32 v83, v86, v87
	v_lshl_add_u64 v[84:85], v[84:85], 0, v[114:115]
	global_store_dwordx4 v[84:85], v[80:83], off nt
	s_nop 1
	v_mul_f32_e32 v81, 0xbfb8aa3b, v68
	v_exp_f32_e32 v81, v81
	v_mul_f32_e32 v80, 0xbfb8aa3b, v76
	v_exp_f32_e32 v80, v80
	v_add_f32_e32 v81, 1.0, v81
	v_rcp_f32_e32 v82, v81
	v_mul_f32_e32 v81, 0xbfb8aa3b, v77
	v_exp_f32_e32 v81, v81
	v_add_f32_e32 v80, 1.0, v80
	v_rcp_f32_e32 v80, v80
	v_add_f32_e32 v81, 1.0, v81
	v_rcp_f32_e32 v81, v81
	s_nop 0
	v_pk_mul_f32 v[76:77], v[76:77], v[80:81]
	s_nop 0
	v_pk_mul_f32 v[72:73], v[76:77], v[72:73]
	v_mul_f32_e32 v76, 0xbfb8aa3b, v69
	v_exp_f32_e32 v76, v76
	s_nop 0
	v_add_f32_e32 v76, 1.0, v76
	v_rcp_f32_e32 v83, v76
	s_nop 0
	v_pk_mul_f32 v[68:69], v[68:69], v[82:83]
	s_nop 0
	v_pk_mul_f32 v[68:69], v[68:69], v[64:65]
	v_mul_f32_e32 v65, 0xbfb8aa3b, v70
	v_exp_f32_e32 v65, v65
	v_mul_f32_e32 v64, 0xbfb8aa3b, v78
	v_exp_f32_e32 v64, v64
	v_add_f32_e32 v65, 1.0, v65
	v_rcp_f32_e32 v76, v65
	v_mul_f32_e32 v65, 0xbfb8aa3b, v79
	v_exp_f32_e32 v65, v65
	v_add_f32_e32 v64, 1.0, v64
	v_rcp_f32_e32 v64, v64
	v_add_f32_e32 v65, 1.0, v65
	v_rcp_f32_e32 v65, v65
	s_nop 0
	v_pk_mul_f32 v[64:65], v[78:79], v[64:65]
	s_nop 0
	v_pk_mul_f32 v[74:75], v[64:65], v[74:75]
	v_mul_f32_e32 v64, 0xbfb8aa3b, v71
	v_exp_f32_e32 v64, v64
	s_nop 0
	v_add_f32_e32 v64, 1.0, v64
	v_rcp_f32_e32 v77, v64
	s_nop 0
	v_pk_mul_f32 v[64:65], v[70:71], v[76:77]
	s_nop 0
	v_pk_mul_f32 v[70:71], v[64:65], v[66:67]
	v_cvt_pk_bf16_f32 v66, v68, v69
	v_or_b32_e32 v68, 48, v142
	v_mad_i64_i32 v[68:69], s[4:5], v68, s18, v[112:113]
	v_cvt_pk_bf16_f32 v64, v72, v73
	v_cvt_pk_bf16_f32 v65, v74, v75
	v_cvt_pk_bf16_f32 v67, v70, v71
	v_lshl_add_u64 v[68:69], v[68:69], 0, v[114:115]
	global_store_dwordx4 v[68:69], v[64:67], off nt
	v_add_u32_e32 v68, 0x80, v142
	s_nop 0
	v_mul_f32_e32 v65, 0xbfb8aa3b, v52
	v_exp_f32_e32 v65, v65
	v_mul_f32_e32 v64, 0xbfb8aa3b, v60
	v_exp_f32_e32 v64, v64
	v_add_f32_e32 v65, 1.0, v65
	v_rcp_f32_e32 v66, v65
	v_mul_f32_e32 v65, 0xbfb8aa3b, v61
	v_exp_f32_e32 v65, v65
	v_add_f32_e32 v64, 1.0, v64
	v_rcp_f32_e32 v64, v64
	v_add_f32_e32 v65, 1.0, v65
	v_rcp_f32_e32 v65, v65
	s_nop 0
	v_pk_mul_f32 v[60:61], v[60:61], v[64:65]
	s_nop 0
	v_pk_mul_f32 v[56:57], v[60:61], v[56:57]
	v_mul_f32_e32 v60, 0xbfb8aa3b, v53
	v_exp_f32_e32 v60, v60
	s_nop 0
	v_add_f32_e32 v60, 1.0, v60
	v_rcp_f32_e32 v67, v60
	s_nop 0
	v_pk_mul_f32 v[52:53], v[52:53], v[66:67]
	s_nop 0
	v_pk_mul_f32 v[52:53], v[52:53], v[48:49]
	v_mul_f32_e32 v49, 0xbfb8aa3b, v54
	v_exp_f32_e32 v49, v49
	v_mul_f32_e32 v48, 0xbfb8aa3b, v62
	v_exp_f32_e32 v48, v48
	v_add_f32_e32 v49, 1.0, v49
	v_rcp_f32_e32 v60, v49
	v_mul_f32_e32 v49, 0xbfb8aa3b, v63
	v_exp_f32_e32 v49, v49
	v_add_f32_e32 v48, 1.0, v48
	v_rcp_f32_e32 v48, v48
	v_add_f32_e32 v49, 1.0, v49
	v_rcp_f32_e32 v49, v49
	s_nop 0
	v_pk_mul_f32 v[48:49], v[62:63], v[48:49]
	s_nop 0
; DI float siluf_(float x) { return x * sigmoidf_(x); }
; #define PG8_WAIT_V(n) asm volatile("s_waitcnt vmcnt(" #n ")" ::: "memory")
; #define PG8_BAR __builtin_amdgcn_s_barrier()
; DI u32x4 pack8v(const f32x4& a, const f32x4& b) { u32x4 w; w.x = pk2(a[0], a[1]); w.y = pk2(a[2], a[3]); w.z = pk2(b[0], b[1]); w.w = pk2(b[2], b[3]); return w; }
; #define PG8_WAIT_V(n) asm volatile("s_waitcnt vmcnt(" #n ")" ::: "memory")
; #define PG8_BAR __builtin_amdgcn_s_barrier()
; template <class Epi>
; DI void gemm_phase(char* smem, const bf16_t* A, int lda, const bf16_t* Bt, int ldb, int K, const Order& S_, const Epi& E) {
;     ...
;     if (!has_next) break;
; #pragma unroll
;     for (int a = 0; a < 2; ++a)
; #pragma unroll
;       for (int b = 0; b < 2; ++b)
; #pragma unroll
;         for (int m = 0; m < 4; ++m)
; #pragma unroll
;           for (int n = 0; n < 2; ++n) acc[a][b][m][n] = (f32x4){0.f, 0.f, 0.f, 0.f};
;     cur = nxt; cA = nA; cB = nB; ++ui;
;   }
;   PG8_WAIT_V(0);
;   if (wr == 0) PG8_BAR;
;   PG8_BAR;
;   DI void operator()(const acc_t& acc, const Unit& u, int wr, int wc, int fr, int fq) const {
;     ...
;     for (int ai = 0; ai < 2; ++ai)
; #pragma unroll
;       for (int m = 0; m < 4; ++m) {
;         f32x4 r0, r1;
; #pragma unroll
;         for (int e = 0; e < 4; ++e) { r0[e] = siluf_(acc[ai][0][m][0][e]) * acc[ai][1][m][0][e]; r1[e] = siluf_(acc[ai][0][m][1][e]) * acc[ai][1][m][1][e]; }
;         *(u32x4*)(G + (size_t)(row0 + ai * HALF + m * 16) * DFF + col0) = pack8v(r0, r1); }
	v_pk_mul_f32 v[58:59], v[48:49], v[58:59]
	v_mul_f32_e32 v48, 0xbfb8aa3b, v55
	v_exp_f32_e32 v48, v48
	s_nop 0
	v_add_f32_e32 v48, 1.0, v48
	v_rcp_f32_e32 v61, v48
	s_nop 0
	v_pk_mul_f32 v[48:49], v[54:55], v[60:61]
	s_nop 0
	v_pk_mul_f32 v[54:55], v[48:49], v[50:51]
	v_cvt_pk_bf16_f32 v50, v52, v53
	v_mad_i64_i32 v[52:53], s[4:5], v68, s18, v[112:113]
	v_cvt_pk_bf16_f32 v48, v56, v57
	v_cvt_pk_bf16_f32 v49, v58, v59
	v_cvt_pk_bf16_f32 v51, v54, v55
	v_lshl_add_u64 v[52:53], v[52:53], 0, v[114:115]
	global_store_dwordx4 v[52:53], v[48:51], off nt
	s_nop 1
	v_mul_f32_e32 v49, 0xbfb8aa3b, v36
	v_exp_f32_e32 v49, v49
	v_mul_f32_e32 v48, 0xbfb8aa3b, v44
	v_exp_f32_e32 v48, v48
	v_add_f32_e32 v49, 1.0, v49
	v_rcp_f32_e32 v50, v49
	v_mul_f32_e32 v49, 0xbfb8aa3b, v45
	v_exp_f32_e32 v49, v49
	v_add_f32_e32 v48, 1.0, v48
	v_rcp_f32_e32 v48, v48
	v_add_f32_e32 v49, 1.0, v49
	v_rcp_f32_e32 v49, v49
	s_nop 0
	v_pk_mul_f32 v[44:45], v[44:45], v[48:49]
	s_nop 0
	v_pk_mul_f32 v[40:41], v[44:45], v[40:41]
	v_mul_f32_e32 v44, 0xbfb8aa3b, v37
	v_exp_f32_e32 v44, v44
	s_nop 0
	v_add_f32_e32 v44, 1.0, v44
	v_rcp_f32_e32 v51, v44
	s_nop 0
	v_pk_mul_f32 v[36:37], v[36:37], v[50:51]
	s_nop 0
	v_pk_mul_f32 v[36:37], v[36:37], v[32:33]
	v_mul_f32_e32 v33, 0xbfb8aa3b, v38
	v_exp_f32_e32 v33, v33
	v_mul_f32_e32 v32, 0xbfb8aa3b, v46
	v_exp_f32_e32 v32, v32
	v_add_f32_e32 v33, 1.0, v33
	v_rcp_f32_e32 v44, v33
	v_mul_f32_e32 v33, 0xbfb8aa3b, v47
	v_exp_f32_e32 v33, v33
	v_add_f32_e32 v32, 1.0, v32
	v_rcp_f32_e32 v32, v32
	v_add_f32_e32 v33, 1.0, v33
	v_rcp_f32_e32 v33, v33
	s_nop 0
	v_pk_mul_f32 v[32:33], v[46:47], v[32:33]
	s_nop 0
	v_pk_mul_f32 v[42:43], v[32:33], v[42:43]
	v_mul_f32_e32 v32, 0xbfb8aa3b, v39
	v_exp_f32_e32 v32, v32
	s_nop 0
	v_add_f32_e32 v32, 1.0, v32
	v_rcp_f32_e32 v45, v32
	s_nop 0
	v_pk_mul_f32 v[32:33], v[38:39], v[44:45]
	s_nop 0
	v_pk_mul_f32 v[38:39], v[32:33], v[34:35]
	v_cvt_pk_bf16_f32 v34, v36, v37
	v_add_u32_e32 v36, 0x90, v142
	v_mad_i64_i32 v[36:37], s[4:5], v36, s18, v[112:113]
	v_cvt_pk_bf16_f32 v32, v40, v41
	v_cvt_pk_bf16_f32 v33, v42, v43
	v_cvt_pk_bf16_f32 v35, v38, v39
	v_lshl_add_u64 v[36:37], v[36:37], 0, v[114:115]
	global_store_dwordx4 v[36:37], v[32:35], off nt
	s_nop 1
	v_mul_f32_e32 v33, 0xbfb8aa3b, v20
	v_exp_f32_e32 v33, v33
	v_mul_f32_e32 v32, 0xbfb8aa3b, v28
	v_exp_f32_e32 v32, v32
	v_add_f32_e32 v33, 1.0, v33
	v_rcp_f32_e32 v34, v33
	v_mul_f32_e32 v33, 0xbfb8aa3b, v29
	v_exp_f32_e32 v33, v33
	v_add_f32_e32 v32, 1.0, v32
	v_rcp_f32_e32 v32, v32
	v_add_f32_e32 v33, 1.0, v33
	v_rcp_f32_e32 v33, v33
	s_nop 0
	v_pk_mul_f32 v[28:29], v[28:29], v[32:33]
	s_nop 0
	v_pk_mul_f32 v[24:25], v[28:29], v[24:25]
	v_mul_f32_e32 v28, 0xbfb8aa3b, v21
	v_exp_f32_e32 v28, v28
	s_nop 0
	v_add_f32_e32 v28, 1.0, v28
	v_rcp_f32_e32 v35, v28
	s_nop 0
	v_pk_mul_f32 v[20:21], v[20:21], v[34:35]
	s_nop 0
	v_pk_mul_f32 v[20:21], v[20:21], v[16:17]
	v_mul_f32_e32 v17, 0xbfb8aa3b, v22
	v_exp_f32_e32 v17, v17
	v_mul_f32_e32 v16, 0xbfb8aa3b, v30
	v_exp_f32_e32 v16, v16
	v_add_f32_e32 v17, 1.0, v17
	v_rcp_f32_e32 v28, v17
	v_mul_f32_e32 v17, 0xbfb8aa3b, v31
	v_exp_f32_e32 v17, v17
	v_add_f32_e32 v16, 1.0, v16
	v_rcp_f32_e32 v16, v16
	v_add_f32_e32 v17, 1.0, v17
	v_rcp_f32_e32 v17, v17
	s_nop 0
	v_pk_mul_f32 v[16:17], v[30:31], v[16:17]
	s_nop 0
	v_pk_mul_f32 v[26:27], v[16:17], v[26:27]
	v_mul_f32_e32 v16, 0xbfb8aa3b, v23
	v_exp_f32_e32 v16, v16
	s_nop 0
	v_add_f32_e32 v16, 1.0, v16
	v_rcp_f32_e32 v29, v16
	s_nop 0
	v_pk_mul_f32 v[16:17], v[22:23], v[28:29]
	s_nop 0
	v_pk_mul_f32 v[22:23], v[16:17], v[18:19]
	v_cvt_pk_bf16_f32 v18, v20, v21
	v_add_u32_e32 v20, 0xa0, v142
	v_mad_i64_i32 v[20:21], s[4:5], v20, s18, v[112:113]
	v_cvt_pk_bf16_f32 v16, v24, v25
	v_cvt_pk_bf16_f32 v17, v26, v27
	v_cvt_pk_bf16_f32 v19, v22, v23
	v_lshl_add_u64 v[20:21], v[20:21], 0, v[114:115]
	global_store_dwordx4 v[20:21], v[16:19], off nt
	s_nop 1
	v_mul_f32_e32 v17, 0xbfb8aa3b, v4
	v_exp_f32_e32 v17, v17
	v_mul_f32_e32 v16, 0xbfb8aa3b, v12
	v_exp_f32_e32 v16, v16
	v_add_f32_e32 v17, 1.0, v17
	v_rcp_f32_e32 v18, v17
	v_mul_f32_e32 v17, 0xbfb8aa3b, v13
	v_exp_f32_e32 v17, v17
	v_add_f32_e32 v16, 1.0, v16
	v_rcp_f32_e32 v16, v16
	v_add_f32_e32 v17, 1.0, v17
	v_rcp_f32_e32 v17, v17
	s_nop 0
	v_pk_mul_f32 v[12:13], v[12:13], v[16:17]
	s_nop 0
	v_pk_mul_f32 v[8:9], v[12:13], v[8:9]
	v_mul_f32_e32 v12, 0xbfb8aa3b, v5
	v_exp_f32_e32 v12, v12
	s_nop 0
	v_add_f32_e32 v12, 1.0, v12
	v_rcp_f32_e32 v19, v12
	s_nop 0
	v_pk_mul_f32 v[4:5], v[4:5], v[18:19]
	s_nop 0
	v_pk_mul_f32 v[4:5], v[4:5], v[0:1]
	v_mul_f32_e32 v1, 0xbfb8aa3b, v6
	v_exp_f32_e32 v1, v1
	v_mul_f32_e32 v0, 0xbfb8aa3b, v14
	v_exp_f32_e32 v0, v0
	v_add_f32_e32 v1, 1.0, v1
	v_rcp_f32_e32 v12, v1
	v_mul_f32_e32 v1, 0xbfb8aa3b, v15
	v_exp_f32_e32 v1, v1
	v_add_f32_e32 v0, 1.0, v0
	v_rcp_f32_e32 v0, v0
	v_add_f32_e32 v1, 1.0, v1
	v_rcp_f32_e32 v1, v1
	s_nop 0
	v_pk_mul_f32 v[0:1], v[14:15], v[0:1]
	s_nop 0
	v_pk_mul_f32 v[10:11], v[0:1], v[10:11]
	v_mul_f32_e32 v0, 0xbfb8aa3b, v7
	v_exp_f32_e32 v0, v0
	s_nop 0
	v_add_f32_e32 v0, 1.0, v0
	v_rcp_f32_e32 v13, v0
	s_nop 0
	v_pk_mul_f32 v[0:1], v[6:7], v[12:13]
	s_nop 0
	v_pk_mul_f32 v[6:7], v[0:1], v[2:3]
	v_cvt_pk_bf16_f32 v2, v4, v5
	v_add_u32_e32 v4, 0xb0, v142
	v_mad_i64_i32 v[4:5], s[4:5], v4, s18, v[112:113]
	v_cvt_pk_bf16_f32 v0, v8, v9
	v_cvt_pk_bf16_f32 v1, v10, v11
	v_cvt_pk_bf16_f32 v3, v6, v7
	v_lshl_add_u64 v[4:5], v[4:5], 0, v[114:115]
	global_store_dwordx4 v[4:5], v[0:3], off nt
	s_cbranch_vccz .LBB0_1854
	s_waitcnt vmcnt(0)
	s_cmpk_gt_u32 s3, 0xff
	s_cbranch_scc1 .LBB0_1862
	s_barrier
